# w_out conversion (t>=256) and the last 512 gate tiles also moved from phase 0 into seam waits (seam 0: +1 w_out tile per wave, seam 1: +1 gate tile for workers<512)
# speedup vs baseline: 1.0196x; 1.0011x over previous
.LBB0_21:
	s_lshr_b32 s95, s56, 6
	s_add_u32 s56, s26, 0x200000
	s_addc_u32 s57, s27, 0
	s_add_u32 s6, s26, 0x1a00000
	s_addc_u32 s7, s27, 0
	s_add_u32 s52, s26, 0x2200000
	s_addc_u32 s53, s27, 0
	s_add_u32 s58, s26, 0x100000
	s_addc_u32 s59, s27, 0
	s_cmp_lt_i32 s28, 1
	s_cselect_b64 s[0:1], -1, 0
	s_cmp_gt_i32 s29, 0
	s_cselect_b64 s[4:5], -1, 0
	s_and_b64 s[60:61], s[0:1], s[4:5]
	s_andn2_b64 vcc, exec, s[60:61]
	v_and_b32_e32 v209, 63, v208
	s_cbranch_vccnz .LBB0_253
	s_lshl_b32 s0, s3, 3
	s_add_i32 s62, s0, s95
	s_lshl_b32 s64, s30, 3
	s_cmpk_gt_i32 s62, 0x18ff
	s_cbranch_scc1 .LBB0_241
	s_lshl_b32 s0, s95, 14
	v_lshrrev_b32_e32 v76, 5, v209
	v_and_b32_e32 v12, 31, v208
	s_add_i32 s4, s0, 0
	v_lshlrev_b32_e32 v8, 2, v12
	v_mul_u32_u24_e32 v0, 0x84, v76
	s_waitcnt lgkmcnt(0)
	s_cmp_lg_u64 s[16:17], 0
	v_add3_u32 v77, s4, v8, v0
	v_lshlrev_b32_e32 v0, 3, v208
	v_mov_b32_e32 v1, 0
	s_cselect_b64 s[0:1], -1, 0
	v_lshrrev_b32_e32 v78, 3, v209
	v_and_b32_e32 v0, 56, v0
	s_cmp_lg_u64 s[10:11], 0
	v_mul_u32_u24_e32 v4, 0x84, v0
	v_lshlrev_b32_e32 v0, 1, v0
	v_lshlrev_b32_e32 v5, 2, v78
	v_mov_b32_e32 v9, v1
	s_cselect_b64 s[66:67], -1, 0
	s_cmp_lg_u64 s[38:39], 0
	s_mov_b32 s5, 0
	v_lshl_add_u64 v[2:3], s[52:53], 0, v[0:1]
	v_add3_u32 v79, s4, v4, v5
	v_or_b32_e32 v80, 8, v78
	v_or_b32_e32 v81, 16, v78
	v_or_b32_e32 v82, 24, v78
	v_lshl_add_u64 v[4:5], s[14:15], 0, v[8:9]
	v_lshl_add_u64 v[6:7], s[6:7], 0, v[0:1]
	v_lshl_add_u64 v[8:9], s[40:41], 0, v[8:9]
	s_cselect_b64 s[14:15], -1, 0
	v_lshl_add_u64 v[10:11], s[56:57], 0, v[0:1]
	s_lshl_b32 s63, s62, 5
	s_lshl_b32 s65, s64, 5
	s_lshl_b32 s74, s62, 7
	s_lshl_b32 s75, s64, 7
	s_movk_i32 s76, 0xca00
	v_lshlrev_b32_e32 v12, 2, v12
	s_movk_i32 s77, 0x5800
	s_movk_i32 s78, 0x7fff
	s_mov_b32 s79, 0xffff0000
	s_movk_i32 s80, 0x6000
	s_xor_b64 s[40:41], s[0:1], -1
	s_xor_b64 s[66:67], s[66:67], -1
	s_mov_b32 s81, s62
	s_branch .LBB0_26

.LBB0_25:
	s_add_i32 s81, s81, s64
	s_add_i32 s63, s63, s65
	s_add_i32 s74, s74, s75
	s_cmpk_gt_i32 s81, 0x18ff
	s_cbranch_scc1 .LBB0_241

.LBB0_253:
	s_cmp_gt_i32 s29, 1
	s_cselect_b64 s[0:1], -1, 0
	s_and_b64 s[4:5], s[60:61], s[0:1]
	s_andn2_b64 vcc, exec, s[4:5]
	s_cbranch_vccnz .LBB0_303
	s_waitcnt vmcnt(0)
	v_cmp_eq_u32_e32 vcc, 0, v208
	s_waitcnt lgkmcnt(0)
	s_barrier
	v_readfirstlane_b32 s3, v208
	s_nop 3
	s_lshr_b32 s3, s3, 6
	s_cmp_eq_u32 s3, 0
	s_cbranch_scc1 .Lmy_cv0_end
	v_readlane_b32 s36, v237, 0
	v_readlane_b32 s37, v237, 1
	s_mul_i32 s4, s2, 7
	s_add_i32 s4, s4, s3
	s_add_i32 s4, s4, -1
	s_lshl_b32 s72, s3, 14
	s_mov_b32 s3, s4
	s_nop 4
	s_load_dwordx4 s[60:63], s[36:37], 0x60
	s_load_dwordx2 s[64:65], s[36:37], 0x70
	s_load_dwordx2 s[98:99], s[36:37], 0x58
	s_load_dwordx2 s[100:101], s[36:37], 0x48
	v_lshrrev_b32_e32 v6, 5, v209
	v_and_b32_e32 v7, 31, v209
	v_mul_u32_u24_e32 v0, 0x1600, v6
	v_add_lshl_u32 v0, v0, v7, 2
	v_lshlrev_b32_e32 v152, 11, v6
	v_add_lshl_u32 v152, v152, v7, 2
	v_mul_u32_u24_e32 v2, 33, v6
	v_add_lshl_u32 v2, v2, v7, 2
	v_add_u32_e32 v2, s72, v2
	v_and_b32_e32 v8, 7, v209
	v_lshrrev_b32_e32 v9, 3, v209
	v_mul_u32_u24_e32 v3, 0x108, v8
	v_add_lshl_u32 v3, v3, v9, 2
	v_add_u32_e32 v3, s72, v3
	v_lshlrev_b32_e32 v4, 12, v9
	v_lshl_add_u32 v4, v8, 4, v4
	v_lshlrev_b32_e32 v5, 5, v8
	s_waitcnt lgkmcnt(0)
	s_add_i32 s66, s3, 256
	s_lshr_b32 vcc_lo, s66, 6
	s_and_b32 vcc_hi, s66, 63
	s_lshl_b32 s70, vcc_lo, 19
	s_lshl_b32 s71, vcc_hi, 7
	s_add_u32 s68, s98, s70
	s_addc_u32 s69, s99, 0
	s_add_u32 s68, s68, s71
	s_addc_u32 s69, s69, 0
	v_mov_b32_e32 v1, v152
	global_load_dword v112, v1, s[68:69] nt
	v_add_u32_e32 v1, 0x4000, v1
	global_load_dword v113, v1, s[68:69] nt
	v_add_u32_e32 v1, 0x4000, v1
	global_load_dword v114, v1, s[68:69] nt
	v_add_u32_e32 v1, 0x4000, v1
	global_load_dword v115, v1, s[68:69] nt
	v_add_u32_e32 v1, 0x4000, v1
	global_load_dword v116, v1, s[68:69] nt
	v_add_u32_e32 v1, 0x4000, v1
	global_load_dword v117, v1, s[68:69] nt
	v_add_u32_e32 v1, 0x4000, v1
	global_load_dword v118, v1, s[68:69] nt
	v_add_u32_e32 v1, 0x4000, v1
	global_load_dword v119, v1, s[68:69] nt
	v_add_u32_e32 v1, 0x4000, v1
	global_load_dword v120, v1, s[68:69] nt
	v_add_u32_e32 v1, 0x4000, v1
	global_load_dword v121, v1, s[68:69] nt
	v_add_u32_e32 v1, 0x4000, v1
	global_load_dword v122, v1, s[68:69] nt
	v_add_u32_e32 v1, 0x4000, v1
	global_load_dword v123, v1, s[68:69] nt
	v_add_u32_e32 v1, 0x4000, v1
	global_load_dword v124, v1, s[68:69] nt
	v_add_u32_e32 v1, 0x4000, v1
	global_load_dword v125, v1, s[68:69] nt
	v_add_u32_e32 v1, 0x4000, v1
	global_load_dword v126, v1, s[68:69] nt
	v_add_u32_e32 v1, 0x4000, v1
	global_load_dword v127, v1, s[68:69] nt
	v_add_u32_e32 v1, 0x4000, v1
	global_load_dword v128, v1, s[68:69] nt
	v_add_u32_e32 v1, 0x4000, v1
	global_load_dword v129, v1, s[68:69] nt
	v_add_u32_e32 v1, 0x4000, v1
	global_load_dword v130, v1, s[68:69] nt
	v_add_u32_e32 v1, 0x4000, v1
	global_load_dword v131, v1, s[68:69] nt
	v_add_u32_e32 v1, 0x4000, v1
	global_load_dword v132, v1, s[68:69] nt
	v_add_u32_e32 v1, 0x4000, v1
	global_load_dword v133, v1, s[68:69] nt
	v_add_u32_e32 v1, 0x4000, v1
	global_load_dword v134, v1, s[68:69] nt
	v_add_u32_e32 v1, 0x4000, v1
	global_load_dword v135, v1, s[68:69] nt
	v_add_u32_e32 v1, 0x4000, v1
	global_load_dword v136, v1, s[68:69] nt
	v_add_u32_e32 v1, 0x4000, v1
	global_load_dword v137, v1, s[68:69] nt
	v_add_u32_e32 v1, 0x4000, v1
	global_load_dword v138, v1, s[68:69] nt
	v_add_u32_e32 v1, 0x4000, v1
	global_load_dword v139, v1, s[68:69] nt
	v_add_u32_e32 v1, 0x4000, v1
	global_load_dword v140, v1, s[68:69] nt
	v_add_u32_e32 v1, 0x4000, v1
	global_load_dword v141, v1, s[68:69] nt
	v_add_u32_e32 v1, 0x4000, v1
	global_load_dword v142, v1, s[68:69] nt
	v_add_u32_e32 v1, 0x4000, v1
	global_load_dword v143, v1, s[68:69] nt
	s_and_b32 s70, vcc_lo, 1
	s_lshl_b32 s70, s70, 8
	s_add_u32 s70, s100, s70
	s_addc_u32 s71, s101, 0
	global_load_dwordx4 v[144:147], v5, s[70:71]
	global_load_dwordx4 v[148:151], v5, s[70:71] offset:16
	s_add_i32 s66, s3, 512
	s_cmpk_ge_u32 s66, 0x1600
	s_cselect_b32 s68, s64, s62
	s_cselect_b32 s69, s65, s63
	s_cselect_b32 s54, 128, 0
	s_cselect_b32 s41, 0x1600, 0
	s_sub_u32 s41, s66, s41
	s_mul_hi_u32 s4, s41, 0xba2e8ba3
	s_lshr_b32 s4, s4, 7
	s_mul_i32 s70, s4, 0xb0
	s_sub_u32 s5, s41, s70
	s_mul_i32 s70, s4, 0x160000
	s_lshl_b32 s71, s5, 7
	s_add_u32 s68, s68, s70
	s_addc_u32 s69, s69, 0
	s_add_u32 s68, s68, s71
	s_addc_u32 s69, s69, 0
	v_mov_b32_e32 v1, v0
	global_load_dword v32, v1, s[68:69] nt
	v_add_u32_e32 v1, 0xb000, v1
	global_load_dword v33, v1, s[68:69] nt
	v_add_u32_e32 v1, 0xb000, v1
	global_load_dword v34, v1, s[68:69] nt
	v_add_u32_e32 v1, 0xb000, v1
	global_load_dword v35, v1, s[68:69] nt
	v_add_u32_e32 v1, 0xb000, v1
	global_load_dword v36, v1, s[68:69] nt
	v_add_u32_e32 v1, 0xb000, v1
	global_load_dword v37, v1, s[68:69] nt
	v_add_u32_e32 v1, 0xb000, v1
	global_load_dword v38, v1, s[68:69] nt
	v_add_u32_e32 v1, 0xb000, v1
	global_load_dword v39, v1, s[68:69] nt
	v_add_u32_e32 v1, 0xb000, v1
	global_load_dword v40, v1, s[68:69] nt
	v_add_u32_e32 v1, 0xb000, v1
	global_load_dword v41, v1, s[68:69] nt
	v_add_u32_e32 v1, 0xb000, v1
	global_load_dword v42, v1, s[68:69] nt
	v_add_u32_e32 v1, 0xb000, v1
	global_load_dword v43, v1, s[68:69] nt
	v_add_u32_e32 v1, 0xb000, v1
	global_load_dword v44, v1, s[68:69] nt
	v_add_u32_e32 v1, 0xb000, v1
	global_load_dword v45, v1, s[68:69] nt
	v_add_u32_e32 v1, 0xb000, v1
	global_load_dword v46, v1, s[68:69] nt
	v_add_u32_e32 v1, 0xb000, v1
	global_load_dword v47, v1, s[68:69] nt
	v_add_u32_e32 v1, 0xb000, v1
	global_load_dword v48, v1, s[68:69] nt
	v_add_u32_e32 v1, 0xb000, v1
	global_load_dword v49, v1, s[68:69] nt
	v_add_u32_e32 v1, 0xb000, v1
	global_load_dword v50, v1, s[68:69] nt
	v_add_u32_e32 v1, 0xb000, v1
	global_load_dword v51, v1, s[68:69] nt
	v_add_u32_e32 v1, 0xb000, v1
	global_load_dword v52, v1, s[68:69] nt
	v_add_u32_e32 v1, 0xb000, v1
	global_load_dword v53, v1, s[68:69] nt
	v_add_u32_e32 v1, 0xb000, v1
	global_load_dword v54, v1, s[68:69] nt
	v_add_u32_e32 v1, 0xb000, v1
	global_load_dword v55, v1, s[68:69] nt
	v_add_u32_e32 v1, 0xb000, v1
	global_load_dword v56, v1, s[68:69] nt
	v_add_u32_e32 v1, 0xb000, v1
	global_load_dword v57, v1, s[68:69] nt
	v_add_u32_e32 v1, 0xb000, v1
	global_load_dword v58, v1, s[68:69] nt
	v_add_u32_e32 v1, 0xb000, v1
	global_load_dword v59, v1, s[68:69] nt
	v_add_u32_e32 v1, 0xb000, v1
	global_load_dword v60, v1, s[68:69] nt
	v_add_u32_e32 v1, 0xb000, v1
	global_load_dword v61, v1, s[68:69] nt
	v_add_u32_e32 v1, 0xb000, v1
	global_load_dword v62, v1, s[68:69] nt
	v_add_u32_e32 v1, 0xb000, v1
	global_load_dword v63, v1, s[68:69] nt
	s_lshl_b32 s70, s4, 8
	s_add_u32 s70, s60, s70
	s_addc_u32 s71, s61, 0
	global_load_dwordx4 v[96:99], v5, s[70:71]
	global_load_dwordx4 v[100:103], v5, s[70:71] offset:16
	s_addk_i32 s66, 0x700
	s_cmpk_ge_u32 s66, 0x1600
	s_cselect_b32 s68, s64, s62
	s_cselect_b32 s69, s65, s63
	s_cselect_b32 s40, 128, 0
	s_cselect_b32 s41, 0x1600, 0
	s_sub_u32 s41, s66, s41
	s_mul_hi_u32 s55, s41, 0xba2e8ba3
	s_lshr_b32 s55, s55, 7
	s_mul_i32 s70, s55, 0xb0
	s_sub_u32 s67, s41, s70
	s_mul_i32 s70, s55, 0x160000
	s_lshl_b32 s71, s67, 7
	s_add_u32 s68, s68, s70
	s_addc_u32 s69, s69, 0
	s_add_u32 s68, s68, s71
	s_addc_u32 s69, s69, 0
	v_mov_b32_e32 v1, v0
	global_load_dword v64, v1, s[68:69] nt
	v_add_u32_e32 v1, 0xb000, v1
	global_load_dword v65, v1, s[68:69] nt
	v_add_u32_e32 v1, 0xb000, v1
	global_load_dword v66, v1, s[68:69] nt
	v_add_u32_e32 v1, 0xb000, v1
	global_load_dword v67, v1, s[68:69] nt
	v_add_u32_e32 v1, 0xb000, v1
	global_load_dword v68, v1, s[68:69] nt
	v_add_u32_e32 v1, 0xb000, v1
	global_load_dword v69, v1, s[68:69] nt
	v_add_u32_e32 v1, 0xb000, v1
	global_load_dword v70, v1, s[68:69] nt
	v_add_u32_e32 v1, 0xb000, v1
	global_load_dword v71, v1, s[68:69] nt
	v_add_u32_e32 v1, 0xb000, v1
	global_load_dword v72, v1, s[68:69] nt
	v_add_u32_e32 v1, 0xb000, v1
	global_load_dword v73, v1, s[68:69] nt
	v_add_u32_e32 v1, 0xb000, v1
	global_load_dword v74, v1, s[68:69] nt
	v_add_u32_e32 v1, 0xb000, v1
	global_load_dword v75, v1, s[68:69] nt
	v_add_u32_e32 v1, 0xb000, v1
	global_load_dword v76, v1, s[68:69] nt
	v_add_u32_e32 v1, 0xb000, v1
	global_load_dword v77, v1, s[68:69] nt
	v_add_u32_e32 v1, 0xb000, v1
	global_load_dword v78, v1, s[68:69] nt
	v_add_u32_e32 v1, 0xb000, v1
	global_load_dword v79, v1, s[68:69] nt
	v_add_u32_e32 v1, 0xb000, v1
	global_load_dword v80, v1, s[68:69] nt
	v_add_u32_e32 v1, 0xb000, v1
	global_load_dword v81, v1, s[68:69] nt
	v_add_u32_e32 v1, 0xb000, v1
	global_load_dword v82, v1, s[68:69] nt
	v_add_u32_e32 v1, 0xb000, v1
	global_load_dword v83, v1, s[68:69] nt
	v_add_u32_e32 v1, 0xb000, v1
	global_load_dword v84, v1, s[68:69] nt
	v_add_u32_e32 v1, 0xb000, v1
	global_load_dword v85, v1, s[68:69] nt
	v_add_u32_e32 v1, 0xb000, v1
	global_load_dword v86, v1, s[68:69] nt
	v_add_u32_e32 v1, 0xb000, v1
	global_load_dword v87, v1, s[68:69] nt
	v_add_u32_e32 v1, 0xb000, v1
	global_load_dword v88, v1, s[68:69] nt
	v_add_u32_e32 v1, 0xb000, v1
	global_load_dword v89, v1, s[68:69] nt
	v_add_u32_e32 v1, 0xb000, v1
	global_load_dword v90, v1, s[68:69] nt
	v_add_u32_e32 v1, 0xb000, v1
	global_load_dword v91, v1, s[68:69] nt
	v_add_u32_e32 v1, 0xb000, v1
	global_load_dword v92, v1, s[68:69] nt
	v_add_u32_e32 v1, 0xb000, v1
	global_load_dword v93, v1, s[68:69] nt
	v_add_u32_e32 v1, 0xb000, v1
	global_load_dword v94, v1, s[68:69] nt
	v_add_u32_e32 v1, 0xb000, v1
	global_load_dword v95, v1, s[68:69] nt
	s_lshl_b32 s70, s55, 8
	s_add_u32 s70, s60, s70
	s_addc_u32 s71, s61, 0
	global_load_dwordx4 v[104:107], v5, s[70:71]
	global_load_dwordx4 v[108:111], v5, s[70:71] offset:16
	s_waitcnt vmcnt(63)
	s_waitcnt lgkmcnt(0)
	ds_write_b32 v2, v112 offset:0
	ds_write_b32 v2, v113 offset:264
	ds_write_b32 v2, v114 offset:528
	ds_write_b32 v2, v115 offset:792
	ds_write_b32 v2, v116 offset:1056
	ds_write_b32 v2, v117 offset:1320
	ds_write_b32 v2, v118 offset:1584
	ds_write_b32 v2, v119 offset:1848
	ds_write_b32 v2, v120 offset:2112
	ds_write_b32 v2, v121 offset:2376
	ds_write_b32 v2, v122 offset:2640
	ds_write_b32 v2, v123 offset:2904
	ds_write_b32 v2, v124 offset:3168
	ds_write_b32 v2, v125 offset:3432
	ds_write_b32 v2, v126 offset:3696
	ds_write_b32 v2, v127 offset:3960
	ds_write_b32 v2, v128 offset:4224
	ds_write_b32 v2, v129 offset:4488
	ds_write_b32 v2, v130 offset:4752
	ds_write_b32 v2, v131 offset:5016
	ds_write_b32 v2, v132 offset:5280
	ds_write_b32 v2, v133 offset:5544
	ds_write_b32 v2, v134 offset:5808
	ds_write_b32 v2, v135 offset:6072
	ds_write_b32 v2, v136 offset:6336
	ds_write_b32 v2, v137 offset:6600
	ds_write_b32 v2, v138 offset:6864
	ds_write_b32 v2, v139 offset:7128
	ds_write_b32 v2, v140 offset:7392
	ds_write_b32 v2, v141 offset:7656
	ds_write_b32 v2, v142 offset:7920
	ds_write_b32 v2, v143 offset:8184
	s_cmp_lt_u32 vcc_lo, 16
	s_cbranch_scc0 .Lmy_cv0_ns
	v_mul_f32_e32 v144, 0x3f4ccccd, v144
	v_mul_f32_e32 v145, 0x3f4ccccd, v145
	v_mul_f32_e32 v146, 0x3f4ccccd, v146
	v_mul_f32_e32 v147, 0x3f4ccccd, v147
	v_mul_f32_e32 v148, 0x3f4ccccd, v148
	v_mul_f32_e32 v149, 0x3f4ccccd, v149
	v_mul_f32_e32 v150, 0x3f4ccccd, v150
	v_mul_f32_e32 v151, 0x3f4ccccd, v151
	s_branch .Lmy_cv0_sd
.Lmy_cv0_ns:
	v_mov_b32_e32 v144, 1.0
	v_mov_b32_e32 v145, 1.0
	v_mov_b32_e32 v146, 1.0
	v_mov_b32_e32 v147, 1.0
	v_mov_b32_e32 v148, 1.0
	v_mov_b32_e32 v149, 1.0
	v_mov_b32_e32 v150, 1.0
	v_mov_b32_e32 v151, 1.0
.Lmy_cv0_sd:
	s_lshl_b32 s70, vcc_hi, 17
	s_lshl_b32 s71, vcc_lo, 7
	s_add_i32 s70, s70, s71
	s_add_u32 s70, s70, 0x1a00000
	s_add_u32 s70, s26, s70
	s_addc_u32 s71, s27, 0
	s_waitcnt lgkmcnt(0)
	ds_read_b32 v10, v3 offset:0
	ds_read_b32 v11, v3 offset:132
	ds_read_b32 v12, v3 offset:264
	ds_read_b32 v13, v3 offset:396
	ds_read_b32 v14, v3 offset:528
	ds_read_b32 v15, v3 offset:660
	ds_read_b32 v16, v3 offset:792
	ds_read_b32 v17, v3 offset:924
	s_waitcnt lgkmcnt(0)
	v_mul_f32_e32 v10, v10, v144
	v_mul_f32_e32 v11, v11, v145
	v_mul_f32_e32 v12, v12, v146
	v_mul_f32_e32 v13, v13, v147
	v_mul_f32_e32 v14, v14, v148
	v_mul_f32_e32 v15, v15, v149
	v_mul_f32_e32 v16, v16, v150
	v_mul_f32_e32 v17, v17, v151
	v_cvt_pk_bf16_f32 v26, v10, v11
	v_cvt_pk_bf16_f32 v27, v12, v13
	v_cvt_pk_bf16_f32 v28, v14, v15
	v_cvt_pk_bf16_f32 v29, v16, v17
	v_mov_b32_e32 v9, v4
	global_store_dwordx4 v9, v[26:29], s[70:71]
	s_nop 1
	ds_read_b32 v10, v3 offset:32
	ds_read_b32 v11, v3 offset:164
	ds_read_b32 v12, v3 offset:296
	ds_read_b32 v13, v3 offset:428
	ds_read_b32 v14, v3 offset:560
	ds_read_b32 v15, v3 offset:692
	ds_read_b32 v16, v3 offset:824
	ds_read_b32 v17, v3 offset:956
	s_waitcnt lgkmcnt(0)
	v_mul_f32_e32 v10, v10, v144
	v_mul_f32_e32 v11, v11, v145
	v_mul_f32_e32 v12, v12, v146
	v_mul_f32_e32 v13, v13, v147
	v_mul_f32_e32 v14, v14, v148
	v_mul_f32_e32 v15, v15, v149
	v_mul_f32_e32 v16, v16, v150
	v_mul_f32_e32 v17, v17, v151
	v_cvt_pk_bf16_f32 v26, v10, v11
	v_cvt_pk_bf16_f32 v27, v12, v13
	v_cvt_pk_bf16_f32 v28, v14, v15
	v_cvt_pk_bf16_f32 v29, v16, v17
	v_add_u32_e32 v9, 0x8000, v9
	global_store_dwordx4 v9, v[26:29], s[70:71]
	s_nop 1
	ds_read_b32 v10, v3 offset:64
	ds_read_b32 v11, v3 offset:196
	ds_read_b32 v12, v3 offset:328
	ds_read_b32 v13, v3 offset:460
	ds_read_b32 v14, v3 offset:592
	ds_read_b32 v15, v3 offset:724
	ds_read_b32 v16, v3 offset:856
	ds_read_b32 v17, v3 offset:988
	s_waitcnt lgkmcnt(0)
	v_mul_f32_e32 v10, v10, v144
	v_mul_f32_e32 v11, v11, v145
	v_mul_f32_e32 v12, v12, v146
	v_mul_f32_e32 v13, v13, v147
	v_mul_f32_e32 v14, v14, v148
	v_mul_f32_e32 v15, v15, v149
	v_mul_f32_e32 v16, v16, v150
	v_mul_f32_e32 v17, v17, v151
	v_cvt_pk_bf16_f32 v26, v10, v11
	v_cvt_pk_bf16_f32 v27, v12, v13
	v_cvt_pk_bf16_f32 v28, v14, v15
	v_cvt_pk_bf16_f32 v29, v16, v17
	v_add_u32_e32 v9, 0x8000, v9
	global_store_dwordx4 v9, v[26:29], s[70:71]
	s_nop 1
	ds_read_b32 v10, v3 offset:96
	ds_read_b32 v11, v3 offset:228
	ds_read_b32 v12, v3 offset:360
	ds_read_b32 v13, v3 offset:492
	ds_read_b32 v14, v3 offset:624
	ds_read_b32 v15, v3 offset:756
	ds_read_b32 v16, v3 offset:888
	ds_read_b32 v17, v3 offset:1020
	s_waitcnt lgkmcnt(0)
	v_mul_f32_e32 v10, v10, v144
	v_mul_f32_e32 v11, v11, v145
	v_mul_f32_e32 v12, v12, v146
	v_mul_f32_e32 v13, v13, v147
	v_mul_f32_e32 v14, v14, v148
	v_mul_f32_e32 v15, v15, v149
	v_mul_f32_e32 v16, v16, v150
	v_mul_f32_e32 v17, v17, v151
	v_cvt_pk_bf16_f32 v26, v10, v11
	v_cvt_pk_bf16_f32 v27, v12, v13
	v_cvt_pk_bf16_f32 v28, v14, v15
	v_cvt_pk_bf16_f32 v29, v16, v17
	v_add_u32_e32 v9, 0x8000, v9
	global_store_dwordx4 v9, v[26:29], s[70:71]
	s_nop 1
	s_waitcnt vmcnt(34)
	s_waitcnt lgkmcnt(0)
	ds_write_b32 v2, v32 offset:0
	ds_write_b32 v2, v33 offset:264
	ds_write_b32 v2, v34 offset:528
	ds_write_b32 v2, v35 offset:792
	ds_write_b32 v2, v36 offset:1056
	ds_write_b32 v2, v37 offset:1320
	ds_write_b32 v2, v38 offset:1584
	ds_write_b32 v2, v39 offset:1848
	ds_write_b32 v2, v40 offset:2112
	ds_write_b32 v2, v41 offset:2376
	ds_write_b32 v2, v42 offset:2640
	ds_write_b32 v2, v43 offset:2904
	ds_write_b32 v2, v44 offset:3168
	ds_write_b32 v2, v45 offset:3432
	ds_write_b32 v2, v46 offset:3696
	ds_write_b32 v2, v47 offset:3960
	ds_write_b32 v2, v48 offset:4224
	ds_write_b32 v2, v49 offset:4488
	ds_write_b32 v2, v50 offset:4752
	ds_write_b32 v2, v51 offset:5016
	ds_write_b32 v2, v52 offset:5280
	ds_write_b32 v2, v53 offset:5544
	ds_write_b32 v2, v54 offset:5808
	ds_write_b32 v2, v55 offset:6072
	ds_write_b32 v2, v56 offset:6336
	ds_write_b32 v2, v57 offset:6600
	ds_write_b32 v2, v58 offset:6864
	ds_write_b32 v2, v59 offset:7128
	ds_write_b32 v2, v60 offset:7392
	ds_write_b32 v2, v61 offset:7656
	ds_write_b32 v2, v62 offset:7920
	ds_write_b32 v2, v63 offset:8184
	s_lshr_b32 s70, s5, 2
	s_lshl_b32 s70, s70, 8
	s_and_b32 s71, s5, 3
	s_lshl_b32 s71, s71, 5
	s_add_i32 s70, s70, s71
	s_add_i32 s70, s70, s54
	s_lshl_b32 s70, s70, 12
	s_lshl_b32 s71, s4, 7
	s_add_i32 s70, s70, s71
	s_add_u32 s70, s70, 0x2200000
	s_add_u32 s70, s26, s70
	s_addc_u32 s71, s27, 0
	s_waitcnt lgkmcnt(0)
	ds_read_b32 v10, v3 offset:0
	ds_read_b32 v11, v3 offset:132
	ds_read_b32 v12, v3 offset:264
	ds_read_b32 v13, v3 offset:396
	ds_read_b32 v14, v3 offset:528
	ds_read_b32 v15, v3 offset:660
	ds_read_b32 v16, v3 offset:792
	ds_read_b32 v17, v3 offset:924
	s_waitcnt lgkmcnt(0)
	v_mul_f32_e32 v10, v10, v96
	v_mul_f32_e32 v11, v11, v97
	v_mul_f32_e32 v12, v12, v98
	v_mul_f32_e32 v13, v13, v99
	v_mul_f32_e32 v14, v14, v100
	v_mul_f32_e32 v15, v15, v101
	v_mul_f32_e32 v16, v16, v102
	v_mul_f32_e32 v17, v17, v103
	v_cvt_pk_bf16_f32 v26, v10, v11
	v_cvt_pk_bf16_f32 v27, v12, v13
	v_cvt_pk_bf16_f32 v28, v14, v15
	v_cvt_pk_bf16_f32 v29, v16, v17
	v_mov_b32_e32 v9, v4
	global_store_dwordx4 v9, v[26:29], s[70:71]
	s_nop 1
	ds_read_b32 v10, v3 offset:32
	ds_read_b32 v11, v3 offset:164
	ds_read_b32 v12, v3 offset:296
	ds_read_b32 v13, v3 offset:428
	ds_read_b32 v14, v3 offset:560
	ds_read_b32 v15, v3 offset:692
	ds_read_b32 v16, v3 offset:824
	ds_read_b32 v17, v3 offset:956
	s_waitcnt lgkmcnt(0)
	v_mul_f32_e32 v10, v10, v96
	v_mul_f32_e32 v11, v11, v97
	v_mul_f32_e32 v12, v12, v98
	v_mul_f32_e32 v13, v13, v99
	v_mul_f32_e32 v14, v14, v100
	v_mul_f32_e32 v15, v15, v101
	v_mul_f32_e32 v16, v16, v102
	v_mul_f32_e32 v17, v17, v103
	v_cvt_pk_bf16_f32 v26, v10, v11
	v_cvt_pk_bf16_f32 v27, v12, v13
	v_cvt_pk_bf16_f32 v28, v14, v15
	v_cvt_pk_bf16_f32 v29, v16, v17
	v_add_u32_e32 v9, 0x8000, v9
	global_store_dwordx4 v9, v[26:29], s[70:71]
	s_nop 1
	ds_read_b32 v10, v3 offset:64
	ds_read_b32 v11, v3 offset:196
	ds_read_b32 v12, v3 offset:328
	ds_read_b32 v13, v3 offset:460
	ds_read_b32 v14, v3 offset:592
	ds_read_b32 v15, v3 offset:724
	ds_read_b32 v16, v3 offset:856
	ds_read_b32 v17, v3 offset:988
	s_waitcnt lgkmcnt(0)
	v_mul_f32_e32 v10, v10, v96
	v_mul_f32_e32 v11, v11, v97
	v_mul_f32_e32 v12, v12, v98
	v_mul_f32_e32 v13, v13, v99
	v_mul_f32_e32 v14, v14, v100
	v_mul_f32_e32 v15, v15, v101
	v_mul_f32_e32 v16, v16, v102
	v_mul_f32_e32 v17, v17, v103
	v_cvt_pk_bf16_f32 v26, v10, v11
	v_cvt_pk_bf16_f32 v27, v12, v13
	v_cvt_pk_bf16_f32 v28, v14, v15
	v_cvt_pk_bf16_f32 v29, v16, v17
	v_add_u32_e32 v9, 0x8000, v9
	global_store_dwordx4 v9, v[26:29], s[70:71]
	s_nop 1
	ds_read_b32 v10, v3 offset:96
	ds_read_b32 v11, v3 offset:228
	ds_read_b32 v12, v3 offset:360
	ds_read_b32 v13, v3 offset:492
	ds_read_b32 v14, v3 offset:624
	ds_read_b32 v15, v3 offset:756
	ds_read_b32 v16, v3 offset:888
	ds_read_b32 v17, v3 offset:1020
	s_waitcnt lgkmcnt(0)
	v_mul_f32_e32 v10, v10, v96
	v_mul_f32_e32 v11, v11, v97
	v_mul_f32_e32 v12, v12, v98
	v_mul_f32_e32 v13, v13, v99
	v_mul_f32_e32 v14, v14, v100
	v_mul_f32_e32 v15, v15, v101
	v_mul_f32_e32 v16, v16, v102
	v_mul_f32_e32 v17, v17, v103
	v_cvt_pk_bf16_f32 v26, v10, v11
	v_cvt_pk_bf16_f32 v27, v12, v13
	v_cvt_pk_bf16_f32 v28, v14, v15
	v_cvt_pk_bf16_f32 v29, v16, v17
	v_add_u32_e32 v9, 0x8000, v9
	global_store_dwordx4 v9, v[26:29], s[70:71]
	s_nop 1
	s_waitcnt vmcnt(0)
	s_waitcnt lgkmcnt(0)
	ds_write_b32 v2, v64 offset:0
	ds_write_b32 v2, v65 offset:264
	ds_write_b32 v2, v66 offset:528
	ds_write_b32 v2, v67 offset:792
	ds_write_b32 v2, v68 offset:1056
	ds_write_b32 v2, v69 offset:1320
	ds_write_b32 v2, v70 offset:1584
	ds_write_b32 v2, v71 offset:1848
	ds_write_b32 v2, v72 offset:2112
	ds_write_b32 v2, v73 offset:2376
	ds_write_b32 v2, v74 offset:2640
	ds_write_b32 v2, v75 offset:2904
	ds_write_b32 v2, v76 offset:3168
	ds_write_b32 v2, v77 offset:3432
	ds_write_b32 v2, v78 offset:3696
	ds_write_b32 v2, v79 offset:3960
	ds_write_b32 v2, v80 offset:4224
	ds_write_b32 v2, v81 offset:4488
	ds_write_b32 v2, v82 offset:4752
	ds_write_b32 v2, v83 offset:5016
	ds_write_b32 v2, v84 offset:5280
	ds_write_b32 v2, v85 offset:5544
	ds_write_b32 v2, v86 offset:5808
	ds_write_b32 v2, v87 offset:6072
	ds_write_b32 v2, v88 offset:6336
	ds_write_b32 v2, v89 offset:6600
	ds_write_b32 v2, v90 offset:6864
	ds_write_b32 v2, v91 offset:7128
	ds_write_b32 v2, v92 offset:7392
	ds_write_b32 v2, v93 offset:7656
	ds_write_b32 v2, v94 offset:7920
	ds_write_b32 v2, v95 offset:8184
	s_lshr_b32 s70, s67, 2
	s_lshl_b32 s70, s70, 8
	s_and_b32 s71, s67, 3
	s_lshl_b32 s71, s71, 5
	s_add_i32 s70, s70, s71
	s_add_i32 s70, s70, s40
	s_lshl_b32 s70, s70, 12
	s_lshl_b32 s71, s55, 7
	s_add_i32 s70, s70, s71
	s_add_u32 s70, s70, 0x2200000
	s_add_u32 s70, s26, s70
	s_addc_u32 s71, s27, 0
	s_waitcnt lgkmcnt(0)
	ds_read_b32 v10, v3 offset:0
	ds_read_b32 v11, v3 offset:132
	ds_read_b32 v12, v3 offset:264
	ds_read_b32 v13, v3 offset:396
	ds_read_b32 v14, v3 offset:528
	ds_read_b32 v15, v3 offset:660
	ds_read_b32 v16, v3 offset:792
	ds_read_b32 v17, v3 offset:924
	s_waitcnt lgkmcnt(0)
	v_mul_f32_e32 v10, v10, v104
	v_mul_f32_e32 v11, v11, v105
	v_mul_f32_e32 v12, v12, v106
	v_mul_f32_e32 v13, v13, v107
	v_mul_f32_e32 v14, v14, v108
	v_mul_f32_e32 v15, v15, v109
	v_mul_f32_e32 v16, v16, v110
	v_mul_f32_e32 v17, v17, v111
	v_cvt_pk_bf16_f32 v26, v10, v11
	v_cvt_pk_bf16_f32 v27, v12, v13
	v_cvt_pk_bf16_f32 v28, v14, v15
	v_cvt_pk_bf16_f32 v29, v16, v17
	v_mov_b32_e32 v9, v4
	global_store_dwordx4 v9, v[26:29], s[70:71]
	s_nop 1
	ds_read_b32 v10, v3 offset:32
	ds_read_b32 v11, v3 offset:164
	ds_read_b32 v12, v3 offset:296
	ds_read_b32 v13, v3 offset:428
	ds_read_b32 v14, v3 offset:560
	ds_read_b32 v15, v3 offset:692
	ds_read_b32 v16, v3 offset:824
	ds_read_b32 v17, v3 offset:956
	s_waitcnt lgkmcnt(0)
	v_mul_f32_e32 v10, v10, v104
	v_mul_f32_e32 v11, v11, v105
	v_mul_f32_e32 v12, v12, v106
	v_mul_f32_e32 v13, v13, v107
	v_mul_f32_e32 v14, v14, v108
	v_mul_f32_e32 v15, v15, v109
	v_mul_f32_e32 v16, v16, v110
	v_mul_f32_e32 v17, v17, v111
	v_cvt_pk_bf16_f32 v26, v10, v11
	v_cvt_pk_bf16_f32 v27, v12, v13
	v_cvt_pk_bf16_f32 v28, v14, v15
	v_cvt_pk_bf16_f32 v29, v16, v17
	v_add_u32_e32 v9, 0x8000, v9
	global_store_dwordx4 v9, v[26:29], s[70:71]
	s_nop 1
	ds_read_b32 v10, v3 offset:64
	ds_read_b32 v11, v3 offset:196
	ds_read_b32 v12, v3 offset:328
	ds_read_b32 v13, v3 offset:460
	ds_read_b32 v14, v3 offset:592
	ds_read_b32 v15, v3 offset:724
	ds_read_b32 v16, v3 offset:856
	ds_read_b32 v17, v3 offset:988
	s_waitcnt lgkmcnt(0)
	v_mul_f32_e32 v10, v10, v104
	v_mul_f32_e32 v11, v11, v105
	v_mul_f32_e32 v12, v12, v106
	v_mul_f32_e32 v13, v13, v107
	v_mul_f32_e32 v14, v14, v108
	v_mul_f32_e32 v15, v15, v109
	v_mul_f32_e32 v16, v16, v110
	v_mul_f32_e32 v17, v17, v111
	v_cvt_pk_bf16_f32 v26, v10, v11
	v_cvt_pk_bf16_f32 v27, v12, v13
	v_cvt_pk_bf16_f32 v28, v14, v15
	v_cvt_pk_bf16_f32 v29, v16, v17
	v_add_u32_e32 v9, 0x8000, v9
	global_store_dwordx4 v9, v[26:29], s[70:71]
	s_nop 1
	ds_read_b32 v10, v3 offset:96
	ds_read_b32 v11, v3 offset:228
	ds_read_b32 v12, v3 offset:360
	ds_read_b32 v13, v3 offset:492
	ds_read_b32 v14, v3 offset:624
	ds_read_b32 v15, v3 offset:756
	ds_read_b32 v16, v3 offset:888
	ds_read_b32 v17, v3 offset:1020
	s_waitcnt lgkmcnt(0)
	v_mul_f32_e32 v10, v10, v104
	v_mul_f32_e32 v11, v11, v105
	v_mul_f32_e32 v12, v12, v106
	v_mul_f32_e32 v13, v13, v107
	v_mul_f32_e32 v14, v14, v108
	v_mul_f32_e32 v15, v15, v109
	v_mul_f32_e32 v16, v16, v110
	v_mul_f32_e32 v17, v17, v111
	v_cvt_pk_bf16_f32 v26, v10, v11
	v_cvt_pk_bf16_f32 v27, v12, v13
	v_cvt_pk_bf16_f32 v28, v14, v15
	v_cvt_pk_bf16_f32 v29, v16, v17
	v_add_u32_e32 v9, 0x8000, v9
	global_store_dwordx4 v9, v[26:29], s[70:71]
	s_nop 1
	s_waitcnt vmcnt(0) lgkmcnt(0)

.LBB0_340:
	s_cmp_gt_u32 s29, 2
	s_cselect_b64 s[0:1], -1, 0
	s_and_b64 s[0:1], s[20:21], s[0:1]
	s_andn2_b64 vcc, exec, s[0:1]
	s_cbranch_vccnz .LBB0_392
	s_waitcnt vmcnt(0)
	v_cmp_eq_u32_e32 vcc, 0, v208
	s_waitcnt vmcnt(0) lgkmcnt(0)
	s_barrier
	v_readfirstlane_b32 s3, v208
	s_nop 3
	s_lshr_b32 s3, s3, 6
	s_cmp_eq_u32 s3, 0
	s_cbranch_scc1 .Lmy_cv1_end
	v_readlane_b32 s36, v237, 0
	v_readlane_b32 s37, v237, 1
	s_mul_i32 s4, s2, 7
	s_add_i32 s4, s4, s3
	s_add_i32 s4, s4, -1
	s_lshl_b32 s72, s3, 14
	s_mov_b32 s3, s4
	s_nop 4
	s_load_dwordx4 s[60:63], s[36:37], 0x60
	s_load_dwordx2 s[64:65], s[36:37], 0x70
	v_lshrrev_b32_e32 v6, 5, v209
	v_and_b32_e32 v7, 31, v209
	v_mul_u32_u24_e32 v0, 0x1600, v6
	v_add_lshl_u32 v0, v0, v7, 2
	v_lshlrev_b32_e32 v152, 11, v6
	v_add_lshl_u32 v152, v152, v7, 2
	v_mul_u32_u24_e32 v2, 33, v6
	v_add_lshl_u32 v2, v2, v7, 2
	v_add_u32_e32 v2, s72, v2
	v_and_b32_e32 v8, 7, v209
	v_lshrrev_b32_e32 v9, 3, v209
	v_mul_u32_u24_e32 v3, 0x108, v8
	v_add_lshl_u32 v3, v3, v9, 2
	v_add_u32_e32 v3, s72, v3
	v_lshlrev_b32_e32 v4, 12, v9
	v_lshl_add_u32 v4, v8, 4, v4
	v_lshlrev_b32_e32 v5, 5, v8
	s_waitcnt lgkmcnt(0)
	s_cmpk_lt_u32 s3, 0x200
	s_cbranch_scc0 .Lmy_cv1_no3a
	s_mov_b32 s66, s3
	s_cmpk_ge_u32 s66, 0x1600
	s_cselect_b32 s68, s64, s62
	s_cselect_b32 s69, s65, s63
	s_cselect_b32 s41, 0x1600, 0
	s_sub_u32 s41, s66, s41
	s_mul_hi_u32 vcc_lo, s41, 0xba2e8ba3
	s_lshr_b32 vcc_lo, vcc_lo, 7
	s_mul_i32 s70, vcc_lo, 0xb0
	s_sub_u32 vcc_hi, s41, s70
	s_mul_i32 s70, vcc_lo, 0x160000
	s_lshl_b32 s71, vcc_hi, 7
	s_add_u32 s68, s68, s70
	s_addc_u32 s69, s69, 0
	s_add_u32 s68, s68, s71
	s_addc_u32 s69, s69, 0
	v_mov_b32_e32 v1, v0
	global_load_dword v112, v1, s[68:69] nt
	v_add_u32_e32 v1, 0xb000, v1
	global_load_dword v113, v1, s[68:69] nt
	v_add_u32_e32 v1, 0xb000, v1
	global_load_dword v114, v1, s[68:69] nt
	v_add_u32_e32 v1, 0xb000, v1
	global_load_dword v115, v1, s[68:69] nt
	v_add_u32_e32 v1, 0xb000, v1
	global_load_dword v116, v1, s[68:69] nt
	v_add_u32_e32 v1, 0xb000, v1
	global_load_dword v117, v1, s[68:69] nt
	v_add_u32_e32 v1, 0xb000, v1
	global_load_dword v118, v1, s[68:69] nt
	v_add_u32_e32 v1, 0xb000, v1
	global_load_dword v119, v1, s[68:69] nt
	v_add_u32_e32 v1, 0xb000, v1
	global_load_dword v120, v1, s[68:69] nt
	v_add_u32_e32 v1, 0xb000, v1
	global_load_dword v121, v1, s[68:69] nt
	v_add_u32_e32 v1, 0xb000, v1
	global_load_dword v122, v1, s[68:69] nt
	v_add_u32_e32 v1, 0xb000, v1
	global_load_dword v123, v1, s[68:69] nt
	v_add_u32_e32 v1, 0xb000, v1
	global_load_dword v124, v1, s[68:69] nt
	v_add_u32_e32 v1, 0xb000, v1
	global_load_dword v125, v1, s[68:69] nt
	v_add_u32_e32 v1, 0xb000, v1
	global_load_dword v126, v1, s[68:69] nt
	v_add_u32_e32 v1, 0xb000, v1
	global_load_dword v127, v1, s[68:69] nt
	v_add_u32_e32 v1, 0xb000, v1
	global_load_dword v128, v1, s[68:69] nt
	v_add_u32_e32 v1, 0xb000, v1
	global_load_dword v129, v1, s[68:69] nt
	v_add_u32_e32 v1, 0xb000, v1
	global_load_dword v130, v1, s[68:69] nt
	v_add_u32_e32 v1, 0xb000, v1
	global_load_dword v131, v1, s[68:69] nt
	v_add_u32_e32 v1, 0xb000, v1
	global_load_dword v132, v1, s[68:69] nt
	v_add_u32_e32 v1, 0xb000, v1
	global_load_dword v133, v1, s[68:69] nt
	v_add_u32_e32 v1, 0xb000, v1
	global_load_dword v134, v1, s[68:69] nt
	v_add_u32_e32 v1, 0xb000, v1
	global_load_dword v135, v1, s[68:69] nt
	v_add_u32_e32 v1, 0xb000, v1
	global_load_dword v136, v1, s[68:69] nt
	v_add_u32_e32 v1, 0xb000, v1
	global_load_dword v137, v1, s[68:69] nt
	v_add_u32_e32 v1, 0xb000, v1
	global_load_dword v138, v1, s[68:69] nt
	v_add_u32_e32 v1, 0xb000, v1
	global_load_dword v139, v1, s[68:69] nt
	v_add_u32_e32 v1, 0xb000, v1
	global_load_dword v140, v1, s[68:69] nt
	v_add_u32_e32 v1, 0xb000, v1
	global_load_dword v141, v1, s[68:69] nt
	v_add_u32_e32 v1, 0xb000, v1
	global_load_dword v142, v1, s[68:69] nt
	v_add_u32_e32 v1, 0xb000, v1
	global_load_dword v143, v1, s[68:69] nt
	s_lshl_b32 s70, vcc_lo, 8
	s_add_u32 s70, s60, s70
	s_addc_u32 s71, s61, 0
	global_load_dwordx4 v[144:147], v5, s[70:71]
	global_load_dwordx4 v[148:151], v5, s[70:71] offset:16
.Lmy_cv1_no3a:
	s_add_i32 s66, s3, 4096
	s_cmpk_ge_u32 s66, 0x1600
	s_cselect_b32 s68, s64, s62
	s_cselect_b32 s69, s65, s63
	s_cselect_b32 s54, 128, 0
	s_cselect_b32 s41, 0x1600, 0
	s_sub_u32 s41, s66, s41
	s_mul_hi_u32 s4, s41, 0xba2e8ba3
	s_lshr_b32 s4, s4, 7
	s_mul_i32 s70, s4, 0xb0
	s_sub_u32 s5, s41, s70
	s_mul_i32 s70, s4, 0x160000
	s_lshl_b32 s71, s5, 7
	s_add_u32 s68, s68, s70
	s_addc_u32 s69, s69, 0
	s_add_u32 s68, s68, s71
	s_addc_u32 s69, s69, 0
	v_mov_b32_e32 v1, v0
	global_load_dword v32, v1, s[68:69] nt
	v_add_u32_e32 v1, 0xb000, v1
	global_load_dword v33, v1, s[68:69] nt
	v_add_u32_e32 v1, 0xb000, v1
	global_load_dword v34, v1, s[68:69] nt
	v_add_u32_e32 v1, 0xb000, v1
	global_load_dword v35, v1, s[68:69] nt
	v_add_u32_e32 v1, 0xb000, v1
	global_load_dword v36, v1, s[68:69] nt
	v_add_u32_e32 v1, 0xb000, v1
	global_load_dword v37, v1, s[68:69] nt
	v_add_u32_e32 v1, 0xb000, v1
	global_load_dword v38, v1, s[68:69] nt
	v_add_u32_e32 v1, 0xb000, v1
	global_load_dword v39, v1, s[68:69] nt
	v_add_u32_e32 v1, 0xb000, v1
	global_load_dword v40, v1, s[68:69] nt
	v_add_u32_e32 v1, 0xb000, v1
	global_load_dword v41, v1, s[68:69] nt
	v_add_u32_e32 v1, 0xb000, v1
	global_load_dword v42, v1, s[68:69] nt
	v_add_u32_e32 v1, 0xb000, v1
	global_load_dword v43, v1, s[68:69] nt
	v_add_u32_e32 v1, 0xb000, v1
	global_load_dword v44, v1, s[68:69] nt
	v_add_u32_e32 v1, 0xb000, v1
	global_load_dword v45, v1, s[68:69] nt
	v_add_u32_e32 v1, 0xb000, v1
	global_load_dword v46, v1, s[68:69] nt
	v_add_u32_e32 v1, 0xb000, v1
	global_load_dword v47, v1, s[68:69] nt
	v_add_u32_e32 v1, 0xb000, v1
	global_load_dword v48, v1, s[68:69] nt
	v_add_u32_e32 v1, 0xb000, v1
	global_load_dword v49, v1, s[68:69] nt
	v_add_u32_e32 v1, 0xb000, v1
	global_load_dword v50, v1, s[68:69] nt
	v_add_u32_e32 v1, 0xb000, v1
	global_load_dword v51, v1, s[68:69] nt
	v_add_u32_e32 v1, 0xb000, v1
	global_load_dword v52, v1, s[68:69] nt
	v_add_u32_e32 v1, 0xb000, v1
	global_load_dword v53, v1, s[68:69] nt
	v_add_u32_e32 v1, 0xb000, v1
	global_load_dword v54, v1, s[68:69] nt
	v_add_u32_e32 v1, 0xb000, v1
	global_load_dword v55, v1, s[68:69] nt
	v_add_u32_e32 v1, 0xb000, v1
	global_load_dword v56, v1, s[68:69] nt
	v_add_u32_e32 v1, 0xb000, v1
	global_load_dword v57, v1, s[68:69] nt
	v_add_u32_e32 v1, 0xb000, v1
	global_load_dword v58, v1, s[68:69] nt
	v_add_u32_e32 v1, 0xb000, v1
	global_load_dword v59, v1, s[68:69] nt
	v_add_u32_e32 v1, 0xb000, v1
	global_load_dword v60, v1, s[68:69] nt
	v_add_u32_e32 v1, 0xb000, v1
	global_load_dword v61, v1, s[68:69] nt
	v_add_u32_e32 v1, 0xb000, v1
	global_load_dword v62, v1, s[68:69] nt
	v_add_u32_e32 v1, 0xb000, v1
	global_load_dword v63, v1, s[68:69] nt
	s_lshl_b32 s70, s4, 8
	s_add_u32 s70, s60, s70
	s_addc_u32 s71, s61, 0
	global_load_dwordx4 v[96:99], v5, s[70:71]
	global_load_dwordx4 v[100:103], v5, s[70:71] offset:16
	s_addk_i32 s66, 0x700
	s_cmpk_ge_u32 s66, 0x1600
	s_cselect_b32 s68, s64, s62
	s_cselect_b32 s69, s65, s63
	s_cselect_b32 s40, 128, 0
	s_cselect_b32 s41, 0x1600, 0
	s_sub_u32 s41, s66, s41
	s_mul_hi_u32 s55, s41, 0xba2e8ba3
	s_lshr_b32 s55, s55, 7
	s_mul_i32 s70, s55, 0xb0
	s_sub_u32 s67, s41, s70
	s_mul_i32 s70, s55, 0x160000
	s_lshl_b32 s71, s67, 7
	s_add_u32 s68, s68, s70
	s_addc_u32 s69, s69, 0
	s_add_u32 s68, s68, s71
	s_addc_u32 s69, s69, 0
	v_mov_b32_e32 v1, v0
	global_load_dword v64, v1, s[68:69] nt
	v_add_u32_e32 v1, 0xb000, v1
	global_load_dword v65, v1, s[68:69] nt
	v_add_u32_e32 v1, 0xb000, v1
	global_load_dword v66, v1, s[68:69] nt
	v_add_u32_e32 v1, 0xb000, v1
	global_load_dword v67, v1, s[68:69] nt
	v_add_u32_e32 v1, 0xb000, v1
	global_load_dword v68, v1, s[68:69] nt
	v_add_u32_e32 v1, 0xb000, v1
	global_load_dword v69, v1, s[68:69] nt
	v_add_u32_e32 v1, 0xb000, v1
	global_load_dword v70, v1, s[68:69] nt
	v_add_u32_e32 v1, 0xb000, v1
	global_load_dword v71, v1, s[68:69] nt
	v_add_u32_e32 v1, 0xb000, v1
	global_load_dword v72, v1, s[68:69] nt
	v_add_u32_e32 v1, 0xb000, v1
	global_load_dword v73, v1, s[68:69] nt
	v_add_u32_e32 v1, 0xb000, v1
	global_load_dword v74, v1, s[68:69] nt
	v_add_u32_e32 v1, 0xb000, v1
	global_load_dword v75, v1, s[68:69] nt
	v_add_u32_e32 v1, 0xb000, v1
	global_load_dword v76, v1, s[68:69] nt
	v_add_u32_e32 v1, 0xb000, v1
	global_load_dword v77, v1, s[68:69] nt
	v_add_u32_e32 v1, 0xb000, v1
	global_load_dword v78, v1, s[68:69] nt
	v_add_u32_e32 v1, 0xb000, v1
	global_load_dword v79, v1, s[68:69] nt
	v_add_u32_e32 v1, 0xb000, v1
	global_load_dword v80, v1, s[68:69] nt
	v_add_u32_e32 v1, 0xb000, v1
	global_load_dword v81, v1, s[68:69] nt
	v_add_u32_e32 v1, 0xb000, v1
	global_load_dword v82, v1, s[68:69] nt
	v_add_u32_e32 v1, 0xb000, v1
	global_load_dword v83, v1, s[68:69] nt
	v_add_u32_e32 v1, 0xb000, v1
	global_load_dword v84, v1, s[68:69] nt
	v_add_u32_e32 v1, 0xb000, v1
	global_load_dword v85, v1, s[68:69] nt
	v_add_u32_e32 v1, 0xb000, v1
	global_load_dword v86, v1, s[68:69] nt
	v_add_u32_e32 v1, 0xb000, v1
	global_load_dword v87, v1, s[68:69] nt
	v_add_u32_e32 v1, 0xb000, v1
	global_load_dword v88, v1, s[68:69] nt
	v_add_u32_e32 v1, 0xb000, v1
	global_load_dword v89, v1, s[68:69] nt
	v_add_u32_e32 v1, 0xb000, v1
	global_load_dword v90, v1, s[68:69] nt
	v_add_u32_e32 v1, 0xb000, v1
	global_load_dword v91, v1, s[68:69] nt
	v_add_u32_e32 v1, 0xb000, v1
	global_load_dword v92, v1, s[68:69] nt
	v_add_u32_e32 v1, 0xb000, v1
	global_load_dword v93, v1, s[68:69] nt
	v_add_u32_e32 v1, 0xb000, v1
	global_load_dword v94, v1, s[68:69] nt
	v_add_u32_e32 v1, 0xb000, v1
	global_load_dword v95, v1, s[68:69] nt
	s_lshl_b32 s70, s55, 8
	s_add_u32 s70, s60, s70
	s_addc_u32 s71, s61, 0
	global_load_dwordx4 v[104:107], v5, s[70:71]
	global_load_dwordx4 v[108:111], v5, s[70:71] offset:16
	s_cmpk_lt_u32 s3, 0x200
	s_cbranch_scc0 .Lmy_cv1_no3b
	s_waitcnt vmcnt(63)
	s_waitcnt lgkmcnt(0)
	ds_write_b32 v2, v112 offset:0
	ds_write_b32 v2, v113 offset:264
	ds_write_b32 v2, v114 offset:528
	ds_write_b32 v2, v115 offset:792
	ds_write_b32 v2, v116 offset:1056
	ds_write_b32 v2, v117 offset:1320
	ds_write_b32 v2, v118 offset:1584
	ds_write_b32 v2, v119 offset:1848
	ds_write_b32 v2, v120 offset:2112
	ds_write_b32 v2, v121 offset:2376
	ds_write_b32 v2, v122 offset:2640
	ds_write_b32 v2, v123 offset:2904
	ds_write_b32 v2, v124 offset:3168
	ds_write_b32 v2, v125 offset:3432
	ds_write_b32 v2, v126 offset:3696
	ds_write_b32 v2, v127 offset:3960
	ds_write_b32 v2, v128 offset:4224
	ds_write_b32 v2, v129 offset:4488
	ds_write_b32 v2, v130 offset:4752
	ds_write_b32 v2, v131 offset:5016
	ds_write_b32 v2, v132 offset:5280
	ds_write_b32 v2, v133 offset:5544
	ds_write_b32 v2, v134 offset:5808
	ds_write_b32 v2, v135 offset:6072
	ds_write_b32 v2, v136 offset:6336
	ds_write_b32 v2, v137 offset:6600
	ds_write_b32 v2, v138 offset:6864
	ds_write_b32 v2, v139 offset:7128
	ds_write_b32 v2, v140 offset:7392
	ds_write_b32 v2, v141 offset:7656
	ds_write_b32 v2, v142 offset:7920
	ds_write_b32 v2, v143 offset:8184
	s_lshr_b32 s70, vcc_hi, 2
	s_lshl_b32 s70, s70, 8
	s_and_b32 s71, vcc_hi, 3
	s_lshl_b32 s71, s71, 5
	s_add_i32 s70, s70, s71
	s_lshl_b32 s70, s70, 12
	s_lshl_b32 s71, vcc_lo, 7
	s_add_i32 s70, s70, s71
	s_add_u32 s70, s70, 0x2200000
	s_add_u32 s70, s26, s70
	s_addc_u32 s71, s27, 0
	s_waitcnt lgkmcnt(0)
	ds_read_b32 v10, v3 offset:0
	ds_read_b32 v11, v3 offset:132
	ds_read_b32 v12, v3 offset:264
	ds_read_b32 v13, v3 offset:396
	ds_read_b32 v14, v3 offset:528
	ds_read_b32 v15, v3 offset:660
	ds_read_b32 v16, v3 offset:792
	ds_read_b32 v17, v3 offset:924
	s_waitcnt lgkmcnt(0)
	v_mul_f32_e32 v10, v10, v144
	v_mul_f32_e32 v11, v11, v145
	v_mul_f32_e32 v12, v12, v146
	v_mul_f32_e32 v13, v13, v147
	v_mul_f32_e32 v14, v14, v148
	v_mul_f32_e32 v15, v15, v149
	v_mul_f32_e32 v16, v16, v150
	v_mul_f32_e32 v17, v17, v151
	v_cvt_pk_bf16_f32 v26, v10, v11
	v_cvt_pk_bf16_f32 v27, v12, v13
	v_cvt_pk_bf16_f32 v28, v14, v15
	v_cvt_pk_bf16_f32 v29, v16, v17
	v_mov_b32_e32 v9, v4
	global_store_dwordx4 v9, v[26:29], s[70:71]
	s_nop 1
	ds_read_b32 v10, v3 offset:32
	ds_read_b32 v11, v3 offset:164
	ds_read_b32 v12, v3 offset:296
	ds_read_b32 v13, v3 offset:428
	ds_read_b32 v14, v3 offset:560
	ds_read_b32 v15, v3 offset:692
	ds_read_b32 v16, v3 offset:824
	ds_read_b32 v17, v3 offset:956
	s_waitcnt lgkmcnt(0)
	v_mul_f32_e32 v10, v10, v144
	v_mul_f32_e32 v11, v11, v145
	v_mul_f32_e32 v12, v12, v146
	v_mul_f32_e32 v13, v13, v147
	v_mul_f32_e32 v14, v14, v148
	v_mul_f32_e32 v15, v15, v149
	v_mul_f32_e32 v16, v16, v150
	v_mul_f32_e32 v17, v17, v151
	v_cvt_pk_bf16_f32 v26, v10, v11
	v_cvt_pk_bf16_f32 v27, v12, v13
	v_cvt_pk_bf16_f32 v28, v14, v15
	v_cvt_pk_bf16_f32 v29, v16, v17
	v_add_u32_e32 v9, 0x8000, v9
	global_store_dwordx4 v9, v[26:29], s[70:71]
	s_nop 1
	ds_read_b32 v10, v3 offset:64
	ds_read_b32 v11, v3 offset:196
	ds_read_b32 v12, v3 offset:328
	ds_read_b32 v13, v3 offset:460
	ds_read_b32 v14, v3 offset:592
	ds_read_b32 v15, v3 offset:724
	ds_read_b32 v16, v3 offset:856
	ds_read_b32 v17, v3 offset:988
	s_waitcnt lgkmcnt(0)
	v_mul_f32_e32 v10, v10, v144
	v_mul_f32_e32 v11, v11, v145
	v_mul_f32_e32 v12, v12, v146
	v_mul_f32_e32 v13, v13, v147
	v_mul_f32_e32 v14, v14, v148
	v_mul_f32_e32 v15, v15, v149
	v_mul_f32_e32 v16, v16, v150
	v_mul_f32_e32 v17, v17, v151
	v_cvt_pk_bf16_f32 v26, v10, v11
	v_cvt_pk_bf16_f32 v27, v12, v13
	v_cvt_pk_bf16_f32 v28, v14, v15
	v_cvt_pk_bf16_f32 v29, v16, v17
	v_add_u32_e32 v9, 0x8000, v9
	global_store_dwordx4 v9, v[26:29], s[70:71]
	s_nop 1
	ds_read_b32 v10, v3 offset:96
	ds_read_b32 v11, v3 offset:228
	ds_read_b32 v12, v3 offset:360
	ds_read_b32 v13, v3 offset:492
	ds_read_b32 v14, v3 offset:624
	ds_read_b32 v15, v3 offset:756
	ds_read_b32 v16, v3 offset:888
	ds_read_b32 v17, v3 offset:1020
	s_waitcnt lgkmcnt(0)
	v_mul_f32_e32 v10, v10, v144
	v_mul_f32_e32 v11, v11, v145
	v_mul_f32_e32 v12, v12, v146
	v_mul_f32_e32 v13, v13, v147
	v_mul_f32_e32 v14, v14, v148
	v_mul_f32_e32 v15, v15, v149
	v_mul_f32_e32 v16, v16, v150
	v_mul_f32_e32 v17, v17, v151
	v_cvt_pk_bf16_f32 v26, v10, v11
	v_cvt_pk_bf16_f32 v27, v12, v13
	v_cvt_pk_bf16_f32 v28, v14, v15
	v_cvt_pk_bf16_f32 v29, v16, v17
	v_add_u32_e32 v9, 0x8000, v9
	global_store_dwordx4 v9, v[26:29], s[70:71]
	s_nop 1
.Lmy_cv1_no3b:
	s_waitcnt vmcnt(34)
	s_waitcnt lgkmcnt(0)
	ds_write_b32 v2, v32 offset:0
	ds_write_b32 v2, v33 offset:264
	ds_write_b32 v2, v34 offset:528
	ds_write_b32 v2, v35 offset:792
	ds_write_b32 v2, v36 offset:1056
	ds_write_b32 v2, v37 offset:1320
	ds_write_b32 v2, v38 offset:1584
	ds_write_b32 v2, v39 offset:1848
	ds_write_b32 v2, v40 offset:2112
	ds_write_b32 v2, v41 offset:2376
	ds_write_b32 v2, v42 offset:2640
	ds_write_b32 v2, v43 offset:2904
	ds_write_b32 v2, v44 offset:3168
	ds_write_b32 v2, v45 offset:3432
	ds_write_b32 v2, v46 offset:3696
	ds_write_b32 v2, v47 offset:3960
	ds_write_b32 v2, v48 offset:4224
	ds_write_b32 v2, v49 offset:4488
	ds_write_b32 v2, v50 offset:4752
	ds_write_b32 v2, v51 offset:5016
	ds_write_b32 v2, v52 offset:5280
	ds_write_b32 v2, v53 offset:5544
	ds_write_b32 v2, v54 offset:5808
	ds_write_b32 v2, v55 offset:6072
	ds_write_b32 v2, v56 offset:6336
	ds_write_b32 v2, v57 offset:6600
	ds_write_b32 v2, v58 offset:6864
	ds_write_b32 v2, v59 offset:7128
	ds_write_b32 v2, v60 offset:7392
	ds_write_b32 v2, v61 offset:7656
	ds_write_b32 v2, v62 offset:7920
	ds_write_b32 v2, v63 offset:8184
	s_lshr_b32 s70, s5, 2
	s_lshl_b32 s70, s70, 8
	s_and_b32 s71, s5, 3
	s_lshl_b32 s71, s71, 5
	s_add_i32 s70, s70, s71
	s_add_i32 s70, s70, s54
	s_lshl_b32 s70, s70, 12
	s_lshl_b32 s71, s4, 7
	s_add_i32 s70, s70, s71
	s_add_u32 s70, s70, 0x2200000
	s_add_u32 s70, s26, s70
	s_addc_u32 s71, s27, 0
	s_waitcnt lgkmcnt(0)
	ds_read_b32 v10, v3 offset:0
	ds_read_b32 v11, v3 offset:132
	ds_read_b32 v12, v3 offset:264
	ds_read_b32 v13, v3 offset:396
	ds_read_b32 v14, v3 offset:528
	ds_read_b32 v15, v3 offset:660
	ds_read_b32 v16, v3 offset:792
	ds_read_b32 v17, v3 offset:924
	s_waitcnt lgkmcnt(0)
	v_mul_f32_e32 v10, v10, v96
	v_mul_f32_e32 v11, v11, v97
	v_mul_f32_e32 v12, v12, v98
	v_mul_f32_e32 v13, v13, v99
	v_mul_f32_e32 v14, v14, v100
	v_mul_f32_e32 v15, v15, v101
	v_mul_f32_e32 v16, v16, v102
	v_mul_f32_e32 v17, v17, v103
	v_cvt_pk_bf16_f32 v26, v10, v11
	v_cvt_pk_bf16_f32 v27, v12, v13
	v_cvt_pk_bf16_f32 v28, v14, v15
	v_cvt_pk_bf16_f32 v29, v16, v17
	v_mov_b32_e32 v9, v4
	global_store_dwordx4 v9, v[26:29], s[70:71]
	s_nop 1
	ds_read_b32 v10, v3 offset:32
	ds_read_b32 v11, v3 offset:164
	ds_read_b32 v12, v3 offset:296
	ds_read_b32 v13, v3 offset:428
	ds_read_b32 v14, v3 offset:560
	ds_read_b32 v15, v3 offset:692
	ds_read_b32 v16, v3 offset:824
	ds_read_b32 v17, v3 offset:956
	s_waitcnt lgkmcnt(0)
	v_mul_f32_e32 v10, v10, v96
	v_mul_f32_e32 v11, v11, v97
	v_mul_f32_e32 v12, v12, v98
	v_mul_f32_e32 v13, v13, v99
	v_mul_f32_e32 v14, v14, v100
	v_mul_f32_e32 v15, v15, v101
	v_mul_f32_e32 v16, v16, v102
	v_mul_f32_e32 v17, v17, v103
	v_cvt_pk_bf16_f32 v26, v10, v11
	v_cvt_pk_bf16_f32 v27, v12, v13
	v_cvt_pk_bf16_f32 v28, v14, v15
	v_cvt_pk_bf16_f32 v29, v16, v17
	v_add_u32_e32 v9, 0x8000, v9
	global_store_dwordx4 v9, v[26:29], s[70:71]
	s_nop 1
	ds_read_b32 v10, v3 offset:64
	ds_read_b32 v11, v3 offset:196
	ds_read_b32 v12, v3 offset:328
	ds_read_b32 v13, v3 offset:460
	ds_read_b32 v14, v3 offset:592
	ds_read_b32 v15, v3 offset:724
	ds_read_b32 v16, v3 offset:856
	ds_read_b32 v17, v3 offset:988
	s_waitcnt lgkmcnt(0)
	v_mul_f32_e32 v10, v10, v96
	v_mul_f32_e32 v11, v11, v97
	v_mul_f32_e32 v12, v12, v98
	v_mul_f32_e32 v13, v13, v99
	v_mul_f32_e32 v14, v14, v100
	v_mul_f32_e32 v15, v15, v101
	v_mul_f32_e32 v16, v16, v102
	v_mul_f32_e32 v17, v17, v103
	v_cvt_pk_bf16_f32 v26, v10, v11
	v_cvt_pk_bf16_f32 v27, v12, v13
	v_cvt_pk_bf16_f32 v28, v14, v15
	v_cvt_pk_bf16_f32 v29, v16, v17
	v_add_u32_e32 v9, 0x8000, v9
	global_store_dwordx4 v9, v[26:29], s[70:71]
	s_nop 1
	ds_read_b32 v10, v3 offset:96
	ds_read_b32 v11, v3 offset:228
	ds_read_b32 v12, v3 offset:360
	ds_read_b32 v13, v3 offset:492
	ds_read_b32 v14, v3 offset:624
	ds_read_b32 v15, v3 offset:756
	ds_read_b32 v16, v3 offset:888
	ds_read_b32 v17, v3 offset:1020
	s_waitcnt lgkmcnt(0)
	v_mul_f32_e32 v10, v10, v96
	v_mul_f32_e32 v11, v11, v97
	v_mul_f32_e32 v12, v12, v98
	v_mul_f32_e32 v13, v13, v99
	v_mul_f32_e32 v14, v14, v100
	v_mul_f32_e32 v15, v15, v101
	v_mul_f32_e32 v16, v16, v102
	v_mul_f32_e32 v17, v17, v103
	v_cvt_pk_bf16_f32 v26, v10, v11
	v_cvt_pk_bf16_f32 v27, v12, v13
	v_cvt_pk_bf16_f32 v28, v14, v15
	v_cvt_pk_bf16_f32 v29, v16, v17
	v_add_u32_e32 v9, 0x8000, v9
	global_store_dwordx4 v9, v[26:29], s[70:71]
	s_nop 1
	s_waitcnt vmcnt(0)
	s_waitcnt lgkmcnt(0)
	ds_write_b32 v2, v64 offset:0
	ds_write_b32 v2, v65 offset:264
	ds_write_b32 v2, v66 offset:528
	ds_write_b32 v2, v67 offset:792
	ds_write_b32 v2, v68 offset:1056
	ds_write_b32 v2, v69 offset:1320
	ds_write_b32 v2, v70 offset:1584
	ds_write_b32 v2, v71 offset:1848
	ds_write_b32 v2, v72 offset:2112
	ds_write_b32 v2, v73 offset:2376
	ds_write_b32 v2, v74 offset:2640
	ds_write_b32 v2, v75 offset:2904
	ds_write_b32 v2, v76 offset:3168
	ds_write_b32 v2, v77 offset:3432
	ds_write_b32 v2, v78 offset:3696
	ds_write_b32 v2, v79 offset:3960
	ds_write_b32 v2, v80 offset:4224
	ds_write_b32 v2, v81 offset:4488
	ds_write_b32 v2, v82 offset:4752
	ds_write_b32 v2, v83 offset:5016
	ds_write_b32 v2, v84 offset:5280
	ds_write_b32 v2, v85 offset:5544
	ds_write_b32 v2, v86 offset:5808
	ds_write_b32 v2, v87 offset:6072
	ds_write_b32 v2, v88 offset:6336
	ds_write_b32 v2, v89 offset:6600
	ds_write_b32 v2, v90 offset:6864
	ds_write_b32 v2, v91 offset:7128
	ds_write_b32 v2, v92 offset:7392
	ds_write_b32 v2, v93 offset:7656
	ds_write_b32 v2, v94 offset:7920
	ds_write_b32 v2, v95 offset:8184
	s_lshr_b32 s70, s67, 2
	s_lshl_b32 s70, s70, 8
	s_and_b32 s71, s67, 3
	s_lshl_b32 s71, s71, 5
	s_add_i32 s70, s70, s71
	s_add_i32 s70, s70, s40
	s_lshl_b32 s70, s70, 12
	s_lshl_b32 s71, s55, 7
	s_add_i32 s70, s70, s71
	s_add_u32 s70, s70, 0x2200000
	s_add_u32 s70, s26, s70
	s_addc_u32 s71, s27, 0
	s_waitcnt lgkmcnt(0)
	ds_read_b32 v10, v3 offset:0
	ds_read_b32 v11, v3 offset:132
	ds_read_b32 v12, v3 offset:264
	ds_read_b32 v13, v3 offset:396
	ds_read_b32 v14, v3 offset:528
	ds_read_b32 v15, v3 offset:660
	ds_read_b32 v16, v3 offset:792
	ds_read_b32 v17, v3 offset:924
	s_waitcnt lgkmcnt(0)
	v_mul_f32_e32 v10, v10, v104
	v_mul_f32_e32 v11, v11, v105
	v_mul_f32_e32 v12, v12, v106
	v_mul_f32_e32 v13, v13, v107
	v_mul_f32_e32 v14, v14, v108
	v_mul_f32_e32 v15, v15, v109
	v_mul_f32_e32 v16, v16, v110
	v_mul_f32_e32 v17, v17, v111
	v_cvt_pk_bf16_f32 v26, v10, v11
	v_cvt_pk_bf16_f32 v27, v12, v13
	v_cvt_pk_bf16_f32 v28, v14, v15
	v_cvt_pk_bf16_f32 v29, v16, v17
	v_mov_b32_e32 v9, v4
	global_store_dwordx4 v9, v[26:29], s[70:71]
	s_nop 1
	ds_read_b32 v10, v3 offset:32
	ds_read_b32 v11, v3 offset:164
	ds_read_b32 v12, v3 offset:296
	ds_read_b32 v13, v3 offset:428
	ds_read_b32 v14, v3 offset:560
	ds_read_b32 v15, v3 offset:692
	ds_read_b32 v16, v3 offset:824
	ds_read_b32 v17, v3 offset:956
	s_waitcnt lgkmcnt(0)
	v_mul_f32_e32 v10, v10, v104
	v_mul_f32_e32 v11, v11, v105
	v_mul_f32_e32 v12, v12, v106
	v_mul_f32_e32 v13, v13, v107
	v_mul_f32_e32 v14, v14, v108
	v_mul_f32_e32 v15, v15, v109
	v_mul_f32_e32 v16, v16, v110
	v_mul_f32_e32 v17, v17, v111
	v_cvt_pk_bf16_f32 v26, v10, v11
	v_cvt_pk_bf16_f32 v27, v12, v13
	v_cvt_pk_bf16_f32 v28, v14, v15
	v_cvt_pk_bf16_f32 v29, v16, v17
	v_add_u32_e32 v9, 0x8000, v9
	global_store_dwordx4 v9, v[26:29], s[70:71]
	s_nop 1
	ds_read_b32 v10, v3 offset:64
	ds_read_b32 v11, v3 offset:196
	ds_read_b32 v12, v3 offset:328
	ds_read_b32 v13, v3 offset:460
	ds_read_b32 v14, v3 offset:592
	ds_read_b32 v15, v3 offset:724
	ds_read_b32 v16, v3 offset:856
	ds_read_b32 v17, v3 offset:988
	s_waitcnt lgkmcnt(0)
	v_mul_f32_e32 v10, v10, v104
	v_mul_f32_e32 v11, v11, v105
	v_mul_f32_e32 v12, v12, v106
	v_mul_f32_e32 v13, v13, v107
	v_mul_f32_e32 v14, v14, v108
	v_mul_f32_e32 v15, v15, v109
	v_mul_f32_e32 v16, v16, v110
	v_mul_f32_e32 v17, v17, v111
	v_cvt_pk_bf16_f32 v26, v10, v11
	v_cvt_pk_bf16_f32 v27, v12, v13
	v_cvt_pk_bf16_f32 v28, v14, v15
	v_cvt_pk_bf16_f32 v29, v16, v17
	v_add_u32_e32 v9, 0x8000, v9
	global_store_dwordx4 v9, v[26:29], s[70:71]
	s_nop 1
	ds_read_b32 v10, v3 offset:96
	ds_read_b32 v11, v3 offset:228
	ds_read_b32 v12, v3 offset:360
	ds_read_b32 v13, v3 offset:492
	ds_read_b32 v14, v3 offset:624
	ds_read_b32 v15, v3 offset:756
	ds_read_b32 v16, v3 offset:888
	ds_read_b32 v17, v3 offset:1020
	s_waitcnt lgkmcnt(0)
	v_mul_f32_e32 v10, v10, v104
	v_mul_f32_e32 v11, v11, v105
	v_mul_f32_e32 v12, v12, v106
	v_mul_f32_e32 v13, v13, v107
	v_mul_f32_e32 v14, v14, v108
	v_mul_f32_e32 v15, v15, v109
	v_mul_f32_e32 v16, v16, v110
	v_mul_f32_e32 v17, v17, v111
	v_cvt_pk_bf16_f32 v26, v10, v11
	v_cvt_pk_bf16_f32 v27, v12, v13
	v_cvt_pk_bf16_f32 v28, v14, v15
	v_cvt_pk_bf16_f32 v29, v16, v17
	v_add_u32_e32 v9, 0x8000, v9
	global_store_dwordx4 v9, v[26:29], s[70:71]
	s_nop 1
	s_waitcnt vmcnt(0) lgkmcnt(0)

.LBB0_475:
	s_cmp_gt_u32 s29, 4
	s_cselect_b64 s[0:1], -1, 0
	s_and_b64 s[0:1], s[36:37], s[0:1]
	s_andn2_b64 vcc, exec, s[0:1]
	s_cbranch_vccnz .LBB0_525
	s_waitcnt vmcnt(0)
	v_cmp_eq_u32_e32 vcc, 0, v208
	s_waitcnt vmcnt(0) lgkmcnt(0)
	s_barrier
	v_readfirstlane_b32 s3, v208
	s_nop 3
	s_lshr_b32 s3, s3, 6
	s_cmp_eq_u32 s3, 0
	s_cbranch_scc1 .Lmy_cv2_end
	v_readlane_b32 s36, v237, 0
	v_readlane_b32 s37, v237, 1
	s_mul_i32 s4, s2, 7
	s_add_i32 s4, s4, s3
	s_add_i32 s4, s4, -1
	s_lshl_b32 s72, s3, 14
	s_mov_b32 s3, s4
	s_nop 4
	s_load_dwordx4 s[60:63], s[36:37], 0x60
	s_load_dwordx2 s[64:65], s[36:37], 0x70
	v_lshrrev_b32_e32 v6, 5, v209
	v_and_b32_e32 v7, 31, v209
	v_mul_u32_u24_e32 v0, 0x1600, v6
	v_add_lshl_u32 v0, v0, v7, 2
	v_lshlrev_b32_e32 v152, 11, v6
	v_add_lshl_u32 v152, v152, v7, 2
	v_mul_u32_u24_e32 v2, 33, v6
	v_add_lshl_u32 v2, v2, v7, 2
	v_add_u32_e32 v2, s72, v2
	v_and_b32_e32 v8, 7, v209
	v_lshrrev_b32_e32 v9, 3, v209
	v_mul_u32_u24_e32 v3, 0x108, v8
	v_add_lshl_u32 v3, v3, v9, 2
	v_add_u32_e32 v3, s72, v3
	v_lshlrev_b32_e32 v4, 12, v9
	v_lshl_add_u32 v4, v8, 4, v4
	v_lshlrev_b32_e32 v5, 5, v8
	s_waitcnt lgkmcnt(0)
	s_add_i32 s66, s3, 7680
	s_cmpk_ge_u32 s66, 0x1600
	s_cselect_b32 s68, s64, s62
	s_cselect_b32 s69, s65, s63
	s_cselect_b32 s54, 128, 0
	s_cselect_b32 s41, 0x1600, 0
	s_sub_u32 s41, s66, s41
	s_mul_hi_u32 s4, s41, 0xba2e8ba3
	s_lshr_b32 s4, s4, 7
	s_mul_i32 s70, s4, 0xb0
	s_sub_u32 s5, s41, s70
	s_mul_i32 s70, s4, 0x160000
	s_lshl_b32 s71, s5, 7
	s_add_u32 s68, s68, s70
	s_addc_u32 s69, s69, 0
	s_add_u32 s68, s68, s71
	s_addc_u32 s69, s69, 0
	v_mov_b32_e32 v1, v0
	global_load_dword v32, v1, s[68:69] nt
	v_add_u32_e32 v1, 0xb000, v1
	global_load_dword v33, v1, s[68:69] nt
	v_add_u32_e32 v1, 0xb000, v1
	global_load_dword v34, v1, s[68:69] nt
	v_add_u32_e32 v1, 0xb000, v1
	global_load_dword v35, v1, s[68:69] nt
	v_add_u32_e32 v1, 0xb000, v1
	global_load_dword v36, v1, s[68:69] nt
	v_add_u32_e32 v1, 0xb000, v1
	global_load_dword v37, v1, s[68:69] nt
	v_add_u32_e32 v1, 0xb000, v1
	global_load_dword v38, v1, s[68:69] nt
	v_add_u32_e32 v1, 0xb000, v1
	global_load_dword v39, v1, s[68:69] nt
	v_add_u32_e32 v1, 0xb000, v1
	global_load_dword v40, v1, s[68:69] nt
	v_add_u32_e32 v1, 0xb000, v1
	global_load_dword v41, v1, s[68:69] nt
	v_add_u32_e32 v1, 0xb000, v1
	global_load_dword v42, v1, s[68:69] nt
	v_add_u32_e32 v1, 0xb000, v1
	global_load_dword v43, v1, s[68:69] nt
	v_add_u32_e32 v1, 0xb000, v1
	global_load_dword v44, v1, s[68:69] nt
	v_add_u32_e32 v1, 0xb000, v1
	global_load_dword v45, v1, s[68:69] nt
	v_add_u32_e32 v1, 0xb000, v1
	global_load_dword v46, v1, s[68:69] nt
	v_add_u32_e32 v1, 0xb000, v1
	global_load_dword v47, v1, s[68:69] nt
	v_add_u32_e32 v1, 0xb000, v1
	global_load_dword v48, v1, s[68:69] nt
	v_add_u32_e32 v1, 0xb000, v1
	global_load_dword v49, v1, s[68:69] nt
	v_add_u32_e32 v1, 0xb000, v1
	global_load_dword v50, v1, s[68:69] nt
	v_add_u32_e32 v1, 0xb000, v1
	global_load_dword v51, v1, s[68:69] nt
	v_add_u32_e32 v1, 0xb000, v1
	global_load_dword v52, v1, s[68:69] nt
	v_add_u32_e32 v1, 0xb000, v1
	global_load_dword v53, v1, s[68:69] nt
	v_add_u32_e32 v1, 0xb000, v1
	global_load_dword v54, v1, s[68:69] nt
	v_add_u32_e32 v1, 0xb000, v1
	global_load_dword v55, v1, s[68:69] nt
	v_add_u32_e32 v1, 0xb000, v1
	global_load_dword v56, v1, s[68:69] nt
	v_add_u32_e32 v1, 0xb000, v1
	global_load_dword v57, v1, s[68:69] nt
	v_add_u32_e32 v1, 0xb000, v1
	global_load_dword v58, v1, s[68:69] nt
	v_add_u32_e32 v1, 0xb000, v1
	global_load_dword v59, v1, s[68:69] nt
	v_add_u32_e32 v1, 0xb000, v1
	global_load_dword v60, v1, s[68:69] nt
	v_add_u32_e32 v1, 0xb000, v1
	global_load_dword v61, v1, s[68:69] nt
	v_add_u32_e32 v1, 0xb000, v1
	global_load_dword v62, v1, s[68:69] nt
	v_add_u32_e32 v1, 0xb000, v1
	global_load_dword v63, v1, s[68:69] nt
	s_lshl_b32 s70, s4, 8
	s_add_u32 s70, s60, s70
	s_addc_u32 s71, s61, 0
	global_load_dwordx4 v[96:99], v5, s[70:71]
	global_load_dwordx4 v[100:103], v5, s[70:71] offset:16
	s_addk_i32 s66, 0x700
	s_cmpk_ge_u32 s66, 0x1600
	s_cselect_b32 s68, s64, s62
	s_cselect_b32 s69, s65, s63
	s_cselect_b32 s40, 128, 0
	s_cselect_b32 s41, 0x1600, 0
	s_sub_u32 s41, s66, s41
	s_mul_hi_u32 s55, s41, 0xba2e8ba3
	s_lshr_b32 s55, s55, 7
	s_mul_i32 s70, s55, 0xb0
	s_sub_u32 s67, s41, s70
	s_mul_i32 s70, s55, 0x160000
	s_lshl_b32 s71, s67, 7
	s_add_u32 s68, s68, s70
	s_addc_u32 s69, s69, 0
	s_add_u32 s68, s68, s71
	s_addc_u32 s69, s69, 0
	v_mov_b32_e32 v1, v0
	global_load_dword v64, v1, s[68:69] nt
	v_add_u32_e32 v1, 0xb000, v1
	global_load_dword v65, v1, s[68:69] nt
	v_add_u32_e32 v1, 0xb000, v1
	global_load_dword v66, v1, s[68:69] nt
	v_add_u32_e32 v1, 0xb000, v1
	global_load_dword v67, v1, s[68:69] nt
	v_add_u32_e32 v1, 0xb000, v1
	global_load_dword v68, v1, s[68:69] nt
	v_add_u32_e32 v1, 0xb000, v1
	global_load_dword v69, v1, s[68:69] nt
	v_add_u32_e32 v1, 0xb000, v1
	global_load_dword v70, v1, s[68:69] nt
	v_add_u32_e32 v1, 0xb000, v1
	global_load_dword v71, v1, s[68:69] nt
	v_add_u32_e32 v1, 0xb000, v1
	global_load_dword v72, v1, s[68:69] nt
	v_add_u32_e32 v1, 0xb000, v1
	global_load_dword v73, v1, s[68:69] nt
	v_add_u32_e32 v1, 0xb000, v1
	global_load_dword v74, v1, s[68:69] nt
	v_add_u32_e32 v1, 0xb000, v1
	global_load_dword v75, v1, s[68:69] nt
	v_add_u32_e32 v1, 0xb000, v1
	global_load_dword v76, v1, s[68:69] nt
	v_add_u32_e32 v1, 0xb000, v1
	global_load_dword v77, v1, s[68:69] nt
	v_add_u32_e32 v1, 0xb000, v1
	global_load_dword v78, v1, s[68:69] nt
	v_add_u32_e32 v1, 0xb000, v1
	global_load_dword v79, v1, s[68:69] nt
	v_add_u32_e32 v1, 0xb000, v1
	global_load_dword v80, v1, s[68:69] nt
	v_add_u32_e32 v1, 0xb000, v1
	global_load_dword v81, v1, s[68:69] nt
	v_add_u32_e32 v1, 0xb000, v1
	global_load_dword v82, v1, s[68:69] nt
	v_add_u32_e32 v1, 0xb000, v1
	global_load_dword v83, v1, s[68:69] nt
	v_add_u32_e32 v1, 0xb000, v1
	global_load_dword v84, v1, s[68:69] nt
	v_add_u32_e32 v1, 0xb000, v1
	global_load_dword v85, v1, s[68:69] nt
	v_add_u32_e32 v1, 0xb000, v1
	global_load_dword v86, v1, s[68:69] nt
	v_add_u32_e32 v1, 0xb000, v1
	global_load_dword v87, v1, s[68:69] nt
	v_add_u32_e32 v1, 0xb000, v1
	global_load_dword v88, v1, s[68:69] nt
	v_add_u32_e32 v1, 0xb000, v1
	global_load_dword v89, v1, s[68:69] nt
	v_add_u32_e32 v1, 0xb000, v1
	global_load_dword v90, v1, s[68:69] nt
	v_add_u32_e32 v1, 0xb000, v1
	global_load_dword v91, v1, s[68:69] nt
	v_add_u32_e32 v1, 0xb000, v1
	global_load_dword v92, v1, s[68:69] nt
	v_add_u32_e32 v1, 0xb000, v1
	global_load_dword v93, v1, s[68:69] nt
	v_add_u32_e32 v1, 0xb000, v1
	global_load_dword v94, v1, s[68:69] nt
	v_add_u32_e32 v1, 0xb000, v1
	global_load_dword v95, v1, s[68:69] nt
	s_lshl_b32 s70, s55, 8
	s_add_u32 s70, s60, s70
	s_addc_u32 s71, s61, 0
	global_load_dwordx4 v[104:107], v5, s[70:71]
	global_load_dwordx4 v[108:111], v5, s[70:71] offset:16
	s_waitcnt vmcnt(34)
	s_waitcnt lgkmcnt(0)
	ds_write_b32 v2, v32 offset:0
	ds_write_b32 v2, v33 offset:264
	ds_write_b32 v2, v34 offset:528
	ds_write_b32 v2, v35 offset:792
	ds_write_b32 v2, v36 offset:1056
	ds_write_b32 v2, v37 offset:1320
	ds_write_b32 v2, v38 offset:1584
	ds_write_b32 v2, v39 offset:1848
	ds_write_b32 v2, v40 offset:2112
	ds_write_b32 v2, v41 offset:2376
	ds_write_b32 v2, v42 offset:2640
	ds_write_b32 v2, v43 offset:2904
	ds_write_b32 v2, v44 offset:3168
	ds_write_b32 v2, v45 offset:3432
	ds_write_b32 v2, v46 offset:3696
	ds_write_b32 v2, v47 offset:3960
	ds_write_b32 v2, v48 offset:4224
	ds_write_b32 v2, v49 offset:4488
	ds_write_b32 v2, v50 offset:4752
	ds_write_b32 v2, v51 offset:5016
	ds_write_b32 v2, v52 offset:5280
	ds_write_b32 v2, v53 offset:5544
	ds_write_b32 v2, v54 offset:5808
	ds_write_b32 v2, v55 offset:6072
	ds_write_b32 v2, v56 offset:6336
	ds_write_b32 v2, v57 offset:6600
	ds_write_b32 v2, v58 offset:6864
	ds_write_b32 v2, v59 offset:7128
	ds_write_b32 v2, v60 offset:7392
	ds_write_b32 v2, v61 offset:7656
	ds_write_b32 v2, v62 offset:7920
	ds_write_b32 v2, v63 offset:8184
	s_lshr_b32 s70, s5, 2
	s_lshl_b32 s70, s70, 8
	s_and_b32 s71, s5, 3
	s_lshl_b32 s71, s71, 5
	s_add_i32 s70, s70, s71
	s_add_i32 s70, s70, s54
	s_lshl_b32 s70, s70, 12
	s_lshl_b32 s71, s4, 7
	s_add_i32 s70, s70, s71
	s_add_u32 s70, s70, 0x2200000
	s_add_u32 s70, s26, s70
	s_addc_u32 s71, s27, 0
	s_waitcnt lgkmcnt(0)
	ds_read_b32 v10, v3 offset:0
	ds_read_b32 v11, v3 offset:132
	ds_read_b32 v12, v3 offset:264
	ds_read_b32 v13, v3 offset:396
	ds_read_b32 v14, v3 offset:528
	ds_read_b32 v15, v3 offset:660
	ds_read_b32 v16, v3 offset:792
	ds_read_b32 v17, v3 offset:924
	s_waitcnt lgkmcnt(0)
	v_mul_f32_e32 v10, v10, v96
	v_mul_f32_e32 v11, v11, v97
	v_mul_f32_e32 v12, v12, v98
	v_mul_f32_e32 v13, v13, v99
	v_mul_f32_e32 v14, v14, v100
	v_mul_f32_e32 v15, v15, v101
	v_mul_f32_e32 v16, v16, v102
	v_mul_f32_e32 v17, v17, v103
	v_cvt_pk_bf16_f32 v26, v10, v11
	v_cvt_pk_bf16_f32 v27, v12, v13
	v_cvt_pk_bf16_f32 v28, v14, v15
	v_cvt_pk_bf16_f32 v29, v16, v17
	v_mov_b32_e32 v9, v4
	global_store_dwordx4 v9, v[26:29], s[70:71]
	s_nop 1
	ds_read_b32 v10, v3 offset:32
	ds_read_b32 v11, v3 offset:164
	ds_read_b32 v12, v3 offset:296
	ds_read_b32 v13, v3 offset:428
	ds_read_b32 v14, v3 offset:560
	ds_read_b32 v15, v3 offset:692
	ds_read_b32 v16, v3 offset:824
	ds_read_b32 v17, v3 offset:956
	s_waitcnt lgkmcnt(0)
	v_mul_f32_e32 v10, v10, v96
	v_mul_f32_e32 v11, v11, v97
	v_mul_f32_e32 v12, v12, v98
	v_mul_f32_e32 v13, v13, v99
	v_mul_f32_e32 v14, v14, v100
	v_mul_f32_e32 v15, v15, v101
	v_mul_f32_e32 v16, v16, v102
	v_mul_f32_e32 v17, v17, v103
	v_cvt_pk_bf16_f32 v26, v10, v11
	v_cvt_pk_bf16_f32 v27, v12, v13
	v_cvt_pk_bf16_f32 v28, v14, v15
	v_cvt_pk_bf16_f32 v29, v16, v17
	v_add_u32_e32 v9, 0x8000, v9
	global_store_dwordx4 v9, v[26:29], s[70:71]
	s_nop 1
	ds_read_b32 v10, v3 offset:64
	ds_read_b32 v11, v3 offset:196
	ds_read_b32 v12, v3 offset:328
	ds_read_b32 v13, v3 offset:460
	ds_read_b32 v14, v3 offset:592
	ds_read_b32 v15, v3 offset:724
	ds_read_b32 v16, v3 offset:856
	ds_read_b32 v17, v3 offset:988
	s_waitcnt lgkmcnt(0)
	v_mul_f32_e32 v10, v10, v96
	v_mul_f32_e32 v11, v11, v97
	v_mul_f32_e32 v12, v12, v98
	v_mul_f32_e32 v13, v13, v99
	v_mul_f32_e32 v14, v14, v100
	v_mul_f32_e32 v15, v15, v101
	v_mul_f32_e32 v16, v16, v102
	v_mul_f32_e32 v17, v17, v103
	v_cvt_pk_bf16_f32 v26, v10, v11
	v_cvt_pk_bf16_f32 v27, v12, v13
	v_cvt_pk_bf16_f32 v28, v14, v15
	v_cvt_pk_bf16_f32 v29, v16, v17
	v_add_u32_e32 v9, 0x8000, v9
	global_store_dwordx4 v9, v[26:29], s[70:71]
	s_nop 1
	ds_read_b32 v10, v3 offset:96
	ds_read_b32 v11, v3 offset:228
	ds_read_b32 v12, v3 offset:360
	ds_read_b32 v13, v3 offset:492
	ds_read_b32 v14, v3 offset:624
	ds_read_b32 v15, v3 offset:756
	ds_read_b32 v16, v3 offset:888
	ds_read_b32 v17, v3 offset:1020
	s_waitcnt lgkmcnt(0)
	v_mul_f32_e32 v10, v10, v96
	v_mul_f32_e32 v11, v11, v97
	v_mul_f32_e32 v12, v12, v98
	v_mul_f32_e32 v13, v13, v99
	v_mul_f32_e32 v14, v14, v100
	v_mul_f32_e32 v15, v15, v101
	v_mul_f32_e32 v16, v16, v102
	v_mul_f32_e32 v17, v17, v103
	v_cvt_pk_bf16_f32 v26, v10, v11
	v_cvt_pk_bf16_f32 v27, v12, v13
	v_cvt_pk_bf16_f32 v28, v14, v15
	v_cvt_pk_bf16_f32 v29, v16, v17
	v_add_u32_e32 v9, 0x8000, v9
	global_store_dwordx4 v9, v[26:29], s[70:71]
	s_nop 1
	s_waitcnt vmcnt(0)
	s_waitcnt lgkmcnt(0)
	ds_write_b32 v2, v64 offset:0
	ds_write_b32 v2, v65 offset:264
	ds_write_b32 v2, v66 offset:528
	ds_write_b32 v2, v67 offset:792
	ds_write_b32 v2, v68 offset:1056
	ds_write_b32 v2, v69 offset:1320
	ds_write_b32 v2, v70 offset:1584
	ds_write_b32 v2, v71 offset:1848
	ds_write_b32 v2, v72 offset:2112
	ds_write_b32 v2, v73 offset:2376
	ds_write_b32 v2, v74 offset:2640
	ds_write_b32 v2, v75 offset:2904
	ds_write_b32 v2, v76 offset:3168
	ds_write_b32 v2, v77 offset:3432
	ds_write_b32 v2, v78 offset:3696
	ds_write_b32 v2, v79 offset:3960
	ds_write_b32 v2, v80 offset:4224
	ds_write_b32 v2, v81 offset:4488
	ds_write_b32 v2, v82 offset:4752
	ds_write_b32 v2, v83 offset:5016
	ds_write_b32 v2, v84 offset:5280
	ds_write_b32 v2, v85 offset:5544
	ds_write_b32 v2, v86 offset:5808
	ds_write_b32 v2, v87 offset:6072
	ds_write_b32 v2, v88 offset:6336
	ds_write_b32 v2, v89 offset:6600
	ds_write_b32 v2, v90 offset:6864
	ds_write_b32 v2, v91 offset:7128
	ds_write_b32 v2, v92 offset:7392
	ds_write_b32 v2, v93 offset:7656
	ds_write_b32 v2, v94 offset:7920
	ds_write_b32 v2, v95 offset:8184
	s_lshr_b32 s70, s67, 2
	s_lshl_b32 s70, s70, 8
	s_and_b32 s71, s67, 3
	s_lshl_b32 s71, s71, 5
	s_add_i32 s70, s70, s71
	s_add_i32 s70, s70, s40
	s_lshl_b32 s70, s70, 12
	s_lshl_b32 s71, s55, 7
	s_add_i32 s70, s70, s71
	s_add_u32 s70, s70, 0x2200000
	s_add_u32 s70, s26, s70
	s_addc_u32 s71, s27, 0
	s_waitcnt lgkmcnt(0)
	ds_read_b32 v10, v3 offset:0
	ds_read_b32 v11, v3 offset:132
	ds_read_b32 v12, v3 offset:264
	ds_read_b32 v13, v3 offset:396
	ds_read_b32 v14, v3 offset:528
	ds_read_b32 v15, v3 offset:660
	ds_read_b32 v16, v3 offset:792
	ds_read_b32 v17, v3 offset:924
	s_waitcnt lgkmcnt(0)
	v_mul_f32_e32 v10, v10, v104
	v_mul_f32_e32 v11, v11, v105
	v_mul_f32_e32 v12, v12, v106
	v_mul_f32_e32 v13, v13, v107
	v_mul_f32_e32 v14, v14, v108
	v_mul_f32_e32 v15, v15, v109
	v_mul_f32_e32 v16, v16, v110
	v_mul_f32_e32 v17, v17, v111
	v_cvt_pk_bf16_f32 v26, v10, v11
	v_cvt_pk_bf16_f32 v27, v12, v13
	v_cvt_pk_bf16_f32 v28, v14, v15
	v_cvt_pk_bf16_f32 v29, v16, v17
	v_mov_b32_e32 v9, v4
	global_store_dwordx4 v9, v[26:29], s[70:71]
	s_nop 1
	ds_read_b32 v10, v3 offset:32
	ds_read_b32 v11, v3 offset:164
	ds_read_b32 v12, v3 offset:296
	ds_read_b32 v13, v3 offset:428
	ds_read_b32 v14, v3 offset:560
	ds_read_b32 v15, v3 offset:692
	ds_read_b32 v16, v3 offset:824
	ds_read_b32 v17, v3 offset:956
	s_waitcnt lgkmcnt(0)
	v_mul_f32_e32 v10, v10, v104
	v_mul_f32_e32 v11, v11, v105
	v_mul_f32_e32 v12, v12, v106
	v_mul_f32_e32 v13, v13, v107
	v_mul_f32_e32 v14, v14, v108
	v_mul_f32_e32 v15, v15, v109
	v_mul_f32_e32 v16, v16, v110
	v_mul_f32_e32 v17, v17, v111
	v_cvt_pk_bf16_f32 v26, v10, v11
	v_cvt_pk_bf16_f32 v27, v12, v13
	v_cvt_pk_bf16_f32 v28, v14, v15
	v_cvt_pk_bf16_f32 v29, v16, v17
	v_add_u32_e32 v9, 0x8000, v9
	global_store_dwordx4 v9, v[26:29], s[70:71]
	s_nop 1
	ds_read_b32 v10, v3 offset:64
	ds_read_b32 v11, v3 offset:196
	ds_read_b32 v12, v3 offset:328
	ds_read_b32 v13, v3 offset:460
	ds_read_b32 v14, v3 offset:592
	ds_read_b32 v15, v3 offset:724
	ds_read_b32 v16, v3 offset:856
	ds_read_b32 v17, v3 offset:988
	s_waitcnt lgkmcnt(0)
	v_mul_f32_e32 v10, v10, v104
	v_mul_f32_e32 v11, v11, v105
	v_mul_f32_e32 v12, v12, v106
	v_mul_f32_e32 v13, v13, v107
	v_mul_f32_e32 v14, v14, v108
	v_mul_f32_e32 v15, v15, v109
	v_mul_f32_e32 v16, v16, v110
	v_mul_f32_e32 v17, v17, v111
	v_cvt_pk_bf16_f32 v26, v10, v11
	v_cvt_pk_bf16_f32 v27, v12, v13
	v_cvt_pk_bf16_f32 v28, v14, v15
	v_cvt_pk_bf16_f32 v29, v16, v17
	v_add_u32_e32 v9, 0x8000, v9
	global_store_dwordx4 v9, v[26:29], s[70:71]
	s_nop 1
	ds_read_b32 v10, v3 offset:96
	ds_read_b32 v11, v3 offset:228
	ds_read_b32 v12, v3 offset:360
	ds_read_b32 v13, v3 offset:492
	ds_read_b32 v14, v3 offset:624
	ds_read_b32 v15, v3 offset:756
	ds_read_b32 v16, v3 offset:888
	ds_read_b32 v17, v3 offset:1020
	s_waitcnt lgkmcnt(0)
	v_mul_f32_e32 v10, v10, v104
	v_mul_f32_e32 v11, v11, v105
	v_mul_f32_e32 v12, v12, v106
	v_mul_f32_e32 v13, v13, v107
	v_mul_f32_e32 v14, v14, v108
	v_mul_f32_e32 v15, v15, v109
	v_mul_f32_e32 v16, v16, v110
	v_mul_f32_e32 v17, v17, v111
	v_cvt_pk_bf16_f32 v26, v10, v11
	v_cvt_pk_bf16_f32 v27, v12, v13
	v_cvt_pk_bf16_f32 v28, v14, v15
	v_cvt_pk_bf16_f32 v29, v16, v17
	v_add_u32_e32 v9, 0x8000, v9
	global_store_dwordx4 v9, v[26:29], s[70:71]
	s_nop 1
	s_waitcnt vmcnt(0) lgkmcnt(0)
